# speedup vs baseline: 1.0087x; 1.0087x over previous
; template <int NT, int BM, int BN, bool PLAIN, int NSTAGE, bool EPI_LDS>
; __device__ __forceinline__ void gemm_tile(const Params& p, const GemmDesc& g, bf16_t* lds, const int tid) {
;     ...
;   const int lane = tid & 63, wave = tid >> 6;
;   const int wm = wave / WN, wn = wave % WN;
;   const int fr = lane & 15, fq = lane >> 4;
;   const int m0 = g.m0, n0 = g.n0;
;   const int r0 = tid >> 3, c0 = tid & 7;
;   unsigned aoff[PLAIN ? 1 : NA];
;   const char* abase = (const char*)g.A;
;   if (PLAIN) {
;     abase = (const char*)(g.A + (long)m0 * g.lda_lo);
;     aoff[0] = (unsigned)((r0 * (int)g.lda_lo + c0 * 8) * 2);
;   } else {
; #pragma unroll
;     for (int i = 0; i < NA; ++i) {
;       int ra = m0 + r0 + RP * i;
;       int rlo = ra & g.rmask; rlo = rlo < g.rclamp ? rlo : g.rclamp;
;       aoff[i] = (unsigned)(((long)rlo * g.lda_lo + (long)(ra >> g.rshift) * g.lda_hi + c0 * 8) * 2);
;     }
;   }
;   const char* bbase = (const char*)(g.Bt + (long)n0 * g.ldb);
;   const unsigned boff = (unsigned)((r0 * (int)g.ldb + c0 * 8) * 2);
;   const long astepP = (long)RP * g.lda_lo * 2, bstepP = (long)RP * g.ldb * 2;
;   u32x4 ra4[NA], rb4[NB];
;   f32x4 acc[MI][NI];
; #pragma unroll
;   for (int i = 0; i < MI; ++i)
; #pragma unroll
;     for (int j = 0; j < NI; ++j) acc[i][j] = f32x4{0.f, 0.f, 0.f, 0.f};
;   const int nk = g.K >> 6;
;     ...
;   constexpr int STAGE_BYTES = (BM + BN) * 128;
;   char* const ldsb = (char*)lds;
;   const unsigned woff = (unsigned)(((r0 >> 4) * 2 + (c0 >> 2)) * 1024 + (((((r0 & 15) ^ (c0 >> 2)) * 64) + (c0 & 3) * 16) ^ (((r0 & 15) >> 3) << 5)));
;   const unsigned roff = (unsigned)(((fr * 64) + fq * 16) ^ ((fr >> 3) << 5));
;   const int roff1d = (int)((((fr ^ 1) * 64 + fq * 16) ^ ((fr >> 3) << 5))) - (int)roff;
;     ...
;     constexpr int CST = BN + 16;
;     bf16_t* ct = lds;
;     const bool relu2 = (g.epi == E_RELU2);
; #pragma unroll
;     for (int mi = 0; mi < MI; ++mi)
; #pragma unroll
;       for (int ni = 0; ni < NI; ++ni) {
;         f32x4 v = acc[mi][ni];
;         if (relu2) {
; #pragma unroll
;           for (int j = 0; j < 4; ++j) { const float r = fmaxf(v[j], 0.f); v[j] = r * r; }
;         }
;         u32x2 w;
;         w[0] = pack2(v[0], v[1]);
;         w[1] = pack2(v[2], v[3]);
;         *(u32x2*)(ct + (wm * WTM + mi * 16 + fr) * CST + wn * WTN + ni * 16 + fq * 4) = w;
.LBB0_883:
	v_readlane_b32 s66, v254, 12
	v_readlane_b32 s67, v254, 13
	s_and_b64 vcc, exec, s[54:55]
	s_cbranch_vccz .LBB0_989
	s_cmp_eq_u32 s39, 7
	s_cselect_b64 s[0:1], -1, 0
	s_and_b64 s[2:3], s[0:1], exec
	s_movk_i32 s2, 0x800
	s_cselect_b32 s6, s2, 0x200
	s_cmp_lg_u32 s39, 0
	s_cselect_b64 s[4:5], -1, 0
	s_and_b64 s[2:3], s[4:5], exec
	s_cselect_b32 s36, s6, 0xa00
	s_cmp_ge_i32 s70, s36
	s_cbranch_scc1 .LBB0_989
	v_ashrrev_i32_e32 v0, 6, v224
	s_cmp_eq_u32 s39, 4
	s_waitcnt vmcnt(12)
	v_lshrrev_b32_e32 v2, 30, v0
	s_cselect_b64 s[6:7], -1, 0
	s_cmp_lg_u32 s39, 4
	v_add_u32_e32 v2, v0, v2
	s_cselect_b64 s[8:9], -1, 0
	s_cmp_lg_u32 s39, 5
	v_ashrrev_i32_e32 v3, 2, v2
	v_and_b32_e32 v2, -4, v2
	v_bfe_u32 v6, v224, 2, 1
	s_mov_b32 s2, 0x3ffffe
	s_cselect_b64 s[10:11], -1, 0
	v_sub_u32_e32 v2, v0, v2
	v_and_or_b32 v0, v0, s2, v6
	s_and_b64 s[2:3], s[0:1], exec
	s_movk_i32 s2, 0x2000
	s_cselect_b32 s80, 0x800, s2
	s_mov_b32 s2, 0x240f4800
	s_cselect_b32 s2, s2, 0x7cf4800
	s_add_u32 s14, s84, s2
	s_addc_u32 s15, s85, 0
	s_and_b64 s[2:3], s[0:1], exec
	s_mov_b32 s2, 0x3880000
	s_cselect_b32 s2, s2, 0x5880000
	v_ashrrev_i32_e32 v178, 3, v224
	v_lshlrev_b32_e32 v7, 4, v224
	s_add_u32 s16, s84, s2
	v_and_b32_e32 v4, 7, v224
	v_bitop3_b32 v6, v178, v6, 15 bitop3:0x6c
	v_and_b32_e32 v7, 48, v7
	s_addc_u32 s17, s85, 0
	v_lshlrev_b32_e32 v179, 3, v4
	v_and_b32_e32 v4, 15, v224
	v_bfe_u32 v5, v224, 4, 2
	v_lshl_or_b32 v6, v6, 6, v7
	v_lshlrev_b32_e32 v7, 2, v178
	s_waitcnt vmcnt(8)
	v_lshlrev_b32_e32 v10, 2, v224
	s_and_b64 s[0:1], s[0:1], exec
	v_and_b32_e32 v7, 32, v7
	v_lshlrev_b32_e32 v8, 6, v4
	v_lshlrev_b32_e32 v9, 4, v5
	v_and_b32_e32 v10, 32, v10
	v_lshlrev_b32_e32 v0, 10, v0
	s_mov_b32 s0, 0x1c0f4800
	v_bitop3_b32 v180, v9, v10, v8 bitop3:0x36
	v_bitop3_b32 v182, v6, v0, v7 bitop3:0xde
	v_lshlrev_b32_e32 v183, 14, v3
	v_lshl_or_b32 v0, v3, 7, v4
	v_lshlrev_b32_e32 v3, 3, v5
	s_cselect_b32 s0, 0x7cf4800, s0
	v_xor_b32_e32 v8, 64, v180
	v_lshlrev_b32_e32 v184, 13, v2
	v_lshl_or_b32 v2, v2, 7, v3
	v_mul_u32_u24_e32 v0, 0x210, v0
	s_cselect_b32 s37, 32, 0x80
	s_cselect_b32 s38, 9, 8
	s_add_u32 s18, s84, s0
	v_sub_u32_e32 v181, v8, v180
	s_mov_b64 s[12:13], s[80:81]
	s_addc_u32 s19, s85, 0
	s_lshl_b32 s39, s70, 2
	v_add_u32_e32 v185, v2, v0
	v_and_b32_e32 v4, 15, v224
	v_bfe_u32 v5, v224, 4, 2
	v_lshrrev_b32_e32 v6, 3, v4
	v_and_b32_e32 v7, 7, v4
	v_bfe_u32 v8, v4, 1, 2
	v_xor_b32_e32 v8, v8, v5
	v_lshlrev_b32_e32 v8, 4, v8
	v_lshl_or_b32 v8, v7, 7, v8
	v_lshl_or_b32 v8, v6, 10, v8
	v_lshl_or_b32 v180, v6, 6, v8
	v_xor_b32_e32 v8, 64, v180
	v_sub_u32_e32 v181, v8, v180
	s_mov_b32 s40, s70
	s_branch .LBB0_887

; template <int NT, int BM, int BN, bool PLAIN, int NSTAGE, bool EPI_LDS>
; __device__ __forceinline__ void gemm_tile(const Params& p, const GemmDesc& g, bf16_t* lds, const int tid) {
;     ...
;     for (int mi = 0; mi < MI; ++mi)
; #pragma unroll
;       for (int ni = 0; ni < NI; ++ni) {
;         f32x4 v = acc[mi][ni];
;         if (relu2) {
; #pragma unroll
;           for (int j = 0; j < 4; ++j) { const float r = fmaxf(v[j], 0.f); v[j] = r * r; }
;         }
;         u32x2 w;
;         w[0] = pack2(v[0], v[1]);
;         w[1] = pack2(v[2], v[3]);
;         *(u32x2*)(ct + (wm * WTM + mi * 16 + fr) * CST + wn * WTN + ni * 16 + fq * 4) = w;
;       }
.LBB0_910:
	v_cvt_pk_bf16_f32 v106, v106, v107
	v_cvt_pk_bf16_f32 v107, v108, v109
	v_add_u32_e32 v0, 0x2100, v185
	s_mov_b64 s[28:29], -1
	s_and_b64 vcc, exec, s[26:27]
	ds_write2_b64 v0, v[114:115], v[106:107] offset1:4
	s_cbranch_vccz .LBB0_912
	v_cvt_pk_bf16_f32 v106, v102, v103
	v_cvt_pk_bf16_f32 v107, v104, v105
	s_mov_b64 s[28:29], 0

; template <int NT, int BM, int BN, bool PLAIN, int NSTAGE, bool EPI_LDS>
; __device__ __forceinline__ void gemm_tile(const Params& p, const GemmDesc& g, bf16_t* lds, const int tid) {
;     ...
;     for (int mi = 0; mi < MI; ++mi)
; #pragma unroll
;       for (int ni = 0; ni < NI; ++ni) {
;         f32x4 v = acc[mi][ni];
;         if (relu2) {
; #pragma unroll
;           for (int j = 0; j < 4; ++j) { const float r = fmaxf(v[j], 0.f); v[j] = r * r; }
;         }
;         u32x2 w;
;         w[0] = pack2(v[0], v[1]);
;         w[1] = pack2(v[2], v[3]);
;         *(u32x2*)(ct + (wm * WTM + mi * 16 + fr) * CST + wn * WTN + ni * 16 + fq * 4) = w;
;       }
.LBB0_914:
	v_cvt_pk_bf16_f32 v98, v98, v99
	v_cvt_pk_bf16_f32 v99, v100, v101
	s_mov_b64 s[28:29], -1
	s_and_b64 vcc, exec, s[26:27]
	ds_write2_b64 v0, v[106:107], v[98:99] offset0:8 offset1:12
	s_cbranch_vccz .LBB0_916
	v_cvt_pk_bf16_f32 v98, v94, v95
	v_cvt_pk_bf16_f32 v99, v96, v97
	s_mov_b64 s[28:29], 0

; template <int NT, int BM, int BN, bool PLAIN, int NSTAGE, bool EPI_LDS>
; __device__ __forceinline__ void gemm_tile(const Params& p, const GemmDesc& g, bf16_t* lds, const int tid) {
;     ...
;     for (int mi = 0; mi < MI; ++mi)
; #pragma unroll
;       for (int ni = 0; ni < NI; ++ni) {
;         f32x4 v = acc[mi][ni];
;         if (relu2) {
; #pragma unroll
;           for (int j = 0; j < 4; ++j) { const float r = fmaxf(v[j], 0.f); v[j] = r * r; }
;         }
;         u32x2 w;
;         w[0] = pack2(v[0], v[1]);
;         w[1] = pack2(v[2], v[3]);
;         *(u32x2*)(ct + (wm * WTM + mi * 16 + fr) * CST + wn * WTN + ni * 16 + fq * 4) = w;
;       }
.LBB0_918:
	v_cvt_pk_bf16_f32 v90, v90, v91
	v_cvt_pk_bf16_f32 v91, v92, v93
	v_add_u32_e32 v0, 0x4200, v185
	s_mov_b64 s[28:29], -1
	s_and_b64 vcc, exec, s[26:27]
	ds_write2_b64 v0, v[98:99], v[90:91] offset1:4
	s_cbranch_vccz .LBB0_920
	v_cvt_pk_bf16_f32 v90, v86, v87
	v_cvt_pk_bf16_f32 v91, v88, v89
	s_mov_b64 s[28:29], 0

; template <int NT, int BM, int BN, bool PLAIN, int NSTAGE, bool EPI_LDS>
; __device__ __forceinline__ void gemm_tile(const Params& p, const GemmDesc& g, bf16_t* lds, const int tid) {
;     ...
;     for (int mi = 0; mi < MI; ++mi)
; #pragma unroll
;       for (int ni = 0; ni < NI; ++ni) {
;         f32x4 v = acc[mi][ni];
;         if (relu2) {
; #pragma unroll
;           for (int j = 0; j < 4; ++j) { const float r = fmaxf(v[j], 0.f); v[j] = r * r; }
;         }
;         u32x2 w;
;         w[0] = pack2(v[0], v[1]);
;         w[1] = pack2(v[2], v[3]);
;         *(u32x2*)(ct + (wm * WTM + mi * 16 + fr) * CST + wn * WTN + ni * 16 + fq * 4) = w;
;       }
.LBB0_922:
	v_cvt_pk_bf16_f32 v82, v82, v83
	v_cvt_pk_bf16_f32 v83, v84, v85
	s_mov_b64 s[28:29], -1
	s_and_b64 vcc, exec, s[26:27]
	ds_write2_b64 v0, v[90:91], v[82:83] offset0:8 offset1:12
	s_cbranch_vccz .LBB0_924
	v_cvt_pk_bf16_f32 v82, v78, v79
	v_cvt_pk_bf16_f32 v83, v80, v81
	s_mov_b64 s[28:29], 0

; template <int NT, int BM, int BN, bool PLAIN, int NSTAGE, bool EPI_LDS>
; __device__ __forceinline__ void gemm_tile(const Params& p, const GemmDesc& g, bf16_t* lds, const int tid) {
;     ...
;     for (int mi = 0; mi < MI; ++mi)
; #pragma unroll
;       for (int ni = 0; ni < NI; ++ni) {
;         f32x4 v = acc[mi][ni];
;         if (relu2) {
; #pragma unroll
;           for (int j = 0; j < 4; ++j) { const float r = fmaxf(v[j], 0.f); v[j] = r * r; }
;         }
;         u32x2 w;
;         w[0] = pack2(v[0], v[1]);
;         w[1] = pack2(v[2], v[3]);
;         *(u32x2*)(ct + (wm * WTM + mi * 16 + fr) * CST + wn * WTN + ni * 16 + fq * 4) = w;
;       }
.LBB0_926:
	v_cvt_pk_bf16_f32 v74, v74, v75
	v_cvt_pk_bf16_f32 v75, v76, v77
	v_add_u32_e32 v0, 0x6300, v185
	s_mov_b64 s[28:29], -1
	s_and_b64 vcc, exec, s[26:27]
	ds_write2_b64 v0, v[82:83], v[74:75] offset1:4
	s_cbranch_vccz .LBB0_928
	v_cvt_pk_bf16_f32 v74, v70, v71
	v_cvt_pk_bf16_f32 v75, v72, v73
	s_mov_b64 s[28:29], 0

; template <int NT, int BM, int BN, bool PLAIN, int NSTAGE, bool EPI_LDS>
; __device__ __forceinline__ void gemm_tile(const Params& p, const GemmDesc& g, bf16_t* lds, const int tid) {
;     ...
;     for (int mi = 0; mi < MI; ++mi)
; #pragma unroll
;       for (int ni = 0; ni < NI; ++ni) {
;         f32x4 v = acc[mi][ni];
;         if (relu2) {
; #pragma unroll
;           for (int j = 0; j < 4; ++j) { const float r = fmaxf(v[j], 0.f); v[j] = r * r; }
;         }
;         u32x2 w;
;         w[0] = pack2(v[0], v[1]);
;         w[1] = pack2(v[2], v[3]);
;         *(u32x2*)(ct + (wm * WTM + mi * 16 + fr) * CST + wn * WTN + ni * 16 + fq * 4) = w;
;       }
.LBB0_930:
	v_cvt_pk_bf16_f32 v66, v66, v67
	v_cvt_pk_bf16_f32 v67, v68, v69
	s_mov_b64 s[28:29], -1
	s_and_b64 vcc, exec, s[26:27]
	ds_write2_b64 v0, v[74:75], v[66:67] offset0:8 offset1:12
	s_cbranch_vccz .LBB0_932
	v_cvt_pk_bf16_f32 v66, v62, v63
	v_cvt_pk_bf16_f32 v67, v64, v65
	s_mov_b64 s[28:29], 0

; template <int NT, int BM, int BN, bool PLAIN, int NSTAGE, bool EPI_LDS>
; __device__ __forceinline__ void gemm_tile(const Params& p, const GemmDesc& g, bf16_t* lds, const int tid) {
;     ...
;     for (int mi = 0; mi < MI; ++mi)
; #pragma unroll
;       for (int ni = 0; ni < NI; ++ni) {
;         f32x4 v = acc[mi][ni];
;         if (relu2) {
; #pragma unroll
;           for (int j = 0; j < 4; ++j) { const float r = fmaxf(v[j], 0.f); v[j] = r * r; }
;         }
;         u32x2 w;
;         w[0] = pack2(v[0], v[1]);
;         w[1] = pack2(v[2], v[3]);
;         *(u32x2*)(ct + (wm * WTM + mi * 16 + fr) * CST + wn * WTN + ni * 16 + fq * 4) = w;
;       }
.LBB0_934:
	v_cvt_pk_bf16_f32 v58, v58, v59
	v_cvt_pk_bf16_f32 v59, v60, v61
	v_add_u32_e32 v0, 0x8400, v185
	s_mov_b64 s[28:29], -1
	s_and_b64 vcc, exec, s[26:27]
	ds_write2_b64 v0, v[66:67], v[58:59] offset1:4
	s_cbranch_vccz .LBB0_936
	v_cvt_pk_bf16_f32 v58, v54, v55
	v_cvt_pk_bf16_f32 v59, v56, v57
	s_mov_b64 s[28:29], 0

; template <int NT, int BM, int BN, bool PLAIN, int NSTAGE, bool EPI_LDS>
; __device__ __forceinline__ void gemm_tile(const Params& p, const GemmDesc& g, bf16_t* lds, const int tid) {
;     ...
;     for (int mi = 0; mi < MI; ++mi)
; #pragma unroll
;       for (int ni = 0; ni < NI; ++ni) {
;         f32x4 v = acc[mi][ni];
;         if (relu2) {
; #pragma unroll
;           for (int j = 0; j < 4; ++j) { const float r = fmaxf(v[j], 0.f); v[j] = r * r; }
;         }
;         u32x2 w;
;         w[0] = pack2(v[0], v[1]);
;         w[1] = pack2(v[2], v[3]);
;         *(u32x2*)(ct + (wm * WTM + mi * 16 + fr) * CST + wn * WTN + ni * 16 + fq * 4) = w;
;       }
.LBB0_942:
	v_cvt_pk_bf16_f32 v42, v42, v43
	v_cvt_pk_bf16_f32 v43, v44, v45
	v_add_u32_e32 v0, 0xa500, v185
	s_mov_b64 s[28:29], -1
	s_and_b64 vcc, exec, s[26:27]
	ds_write2_b64 v0, v[50:51], v[42:43] offset1:4
	s_cbranch_vccz .LBB0_944
	v_cvt_pk_bf16_f32 v42, v38, v39
	v_cvt_pk_bf16_f32 v43, v40, v41
	s_mov_b64 s[28:29], 0

; template <int NT, int BM, int BN, bool PLAIN, int NSTAGE, bool EPI_LDS>
; __device__ __forceinline__ void gemm_tile(const Params& p, const GemmDesc& g, bf16_t* lds, const int tid) {
;     ...
;     for (int mi = 0; mi < MI; ++mi)
; #pragma unroll
;       for (int ni = 0; ni < NI; ++ni) {
;         f32x4 v = acc[mi][ni];
;         if (relu2) {
; #pragma unroll
;           for (int j = 0; j < 4; ++j) { const float r = fmaxf(v[j], 0.f); v[j] = r * r; }
;         }
;         u32x2 w;
;         w[0] = pack2(v[0], v[1]);
;         w[1] = pack2(v[2], v[3]);
;         *(u32x2*)(ct + (wm * WTM + mi * 16 + fr) * CST + wn * WTN + ni * 16 + fq * 4) = w;
;       }
.LBB0_946:
	v_cvt_pk_bf16_f32 v34, v34, v35
	v_cvt_pk_bf16_f32 v35, v36, v37
	s_mov_b64 s[28:29], -1
	s_and_b64 vcc, exec, s[26:27]
	ds_write2_b64 v0, v[42:43], v[34:35] offset0:8 offset1:12
	s_cbranch_vccz .LBB0_948
	v_cvt_pk_bf16_f32 v34, v30, v31
	v_cvt_pk_bf16_f32 v35, v32, v33
	s_mov_b64 s[28:29], 0

; template <int NT, int BM, int BN, bool PLAIN, int NSTAGE, bool EPI_LDS>
; __device__ __forceinline__ void gemm_tile(const Params& p, const GemmDesc& g, bf16_t* lds, const int tid) {
;     ...
;     for (int mi = 0; mi < MI; ++mi)
; #pragma unroll
;       for (int ni = 0; ni < NI; ++ni) {
;         f32x4 v = acc[mi][ni];
;         if (relu2) {
; #pragma unroll
;           for (int j = 0; j < 4; ++j) { const float r = fmaxf(v[j], 0.f); v[j] = r * r; }
;         }
;         u32x2 w;
;         w[0] = pack2(v[0], v[1]);
;         w[1] = pack2(v[2], v[3]);
;         *(u32x2*)(ct + (wm * WTM + mi * 16 + fr) * CST + wn * WTN + ni * 16 + fq * 4) = w;
;       }
.LBB0_950:
	v_cvt_pk_bf16_f32 v26, v26, v27
	v_cvt_pk_bf16_f32 v27, v28, v29
	v_add_u32_e32 v0, 0xc600, v185
	s_mov_b64 s[28:29], -1
	s_and_b64 vcc, exec, s[26:27]
	ds_write2_b64 v0, v[34:35], v[26:27] offset1:4
	s_cbranch_vccz .LBB0_952
	v_cvt_pk_bf16_f32 v26, v22, v23
	v_cvt_pk_bf16_f32 v27, v24, v25
	s_mov_b64 s[28:29], 0

; template <int NT, int BM, int BN, bool PLAIN, int NSTAGE, bool EPI_LDS>
; __device__ __forceinline__ void gemm_tile(const Params& p, const GemmDesc& g, bf16_t* lds, const int tid) {
;     ...
;     for (int mi = 0; mi < MI; ++mi)
; #pragma unroll
;       for (int ni = 0; ni < NI; ++ni) {
;         f32x4 v = acc[mi][ni];
;         if (relu2) {
; #pragma unroll
;           for (int j = 0; j < 4; ++j) { const float r = fmaxf(v[j], 0.f); v[j] = r * r; }
;         }
;         u32x2 w;
;         w[0] = pack2(v[0], v[1]);
;         w[1] = pack2(v[2], v[3]);
;         *(u32x2*)(ct + (wm * WTM + mi * 16 + fr) * CST + wn * WTN + ni * 16 + fq * 4) = w;
;       }
.LBB0_954:
	v_cvt_pk_bf16_f32 v18, v18, v19
	v_cvt_pk_bf16_f32 v19, v20, v21
	s_mov_b64 s[28:29], -1
	s_and_b64 vcc, exec, s[26:27]
	ds_write2_b64 v0, v[26:27], v[18:19] offset0:8 offset1:12
	s_cbranch_vccz .LBB0_956
	v_cvt_pk_bf16_f32 v18, v14, v15
	v_cvt_pk_bf16_f32 v19, v16, v17
	s_mov_b64 s[28:29], 0

; template <int NT, int BM, int BN, bool PLAIN, int NSTAGE, bool EPI_LDS>
; __device__ __forceinline__ void gemm_tile(const Params& p, const GemmDesc& g, bf16_t* lds, const int tid) {
;     ...
;     for (int mi = 0; mi < MI; ++mi)
; #pragma unroll
;       for (int ni = 0; ni < NI; ++ni) {
;         f32x4 v = acc[mi][ni];
;         if (relu2) {
; #pragma unroll
;           for (int j = 0; j < 4; ++j) { const float r = fmaxf(v[j], 0.f); v[j] = r * r; }
;         }
;         u32x2 w;
;         w[0] = pack2(v[0], v[1]);
;         w[1] = pack2(v[2], v[3]);
;         *(u32x2*)(ct + (wm * WTM + mi * 16 + fr) * CST + wn * WTN + ni * 16 + fq * 4) = w;
;       }
.LBB0_958:
	v_cvt_pk_bf16_f32 v10, v10, v11
	v_cvt_pk_bf16_f32 v11, v12, v13
	v_add_u32_e32 v0, 0xe700, v185
	s_mov_b64 s[28:29], -1
	s_and_b64 vcc, exec, s[26:27]
	ds_write2_b64 v0, v[18:19], v[10:11] offset1:4
	s_cbranch_vccz .LBB0_960
	v_cvt_pk_bf16_f32 v10, v2, v3
	v_cvt_pk_bf16_f32 v11, v4, v5
	s_mov_b64 s[28:29], 0

; __device__ __forceinline__ float sigmoid_f(float x) { return 1.f / (1.f + __expf(-x)); }
; template <int NT, int BM, int BN, bool PLAIN, int NSTAGE, bool EPI_LDS>
; __device__ __forceinline__ void gemm_tile(const Params& p, const GemmDesc& g, bf16_t* lds, const int tid) {
;     ...
;         *(u32x2*)(ct + (wm * WTM + mi * 16 + fr) * CST + wn * WTN + ni * 16 + fq * 4) = w;
;       }
;     __syncthreads();
;     constexpr int PPR = BN / 8;
;     constexpr int NIT = BM * PPR / NT;
;     bf16_t* o = (bf16_t*)g.out;
;     const long ldo = (g.epi == E_PROJ) ? LDP : (g.epi == E_RELU2 ? 8192 : 2048);
;     const int gcol = COL_BG + g.auxi * 2048;
; #pragma unroll 4
;     for (int i = 0; i < NIT; ++i) {
;       const int id = tid + NT * i;
;       const int row = id / PPR, pc = id % PPR;
;       u32x4 v = *(const u32x4*)(ct + row * CST + pc * 8);
;       bf16_t* op = o + (long)(m0e + row) * ldo + n0e + pc * 8;
;       if (g.epi == E_MERGE0 || g.epi == E_MERGEN) {
;         const u32x4 gt = *(const u32x4*)(((bf16_t*)(p.ws + OFF_proj)) + (long)(m0e + row) * LDP + gcol + n0e + pc * 8);
;         u32x4 pv = u32x4{0u, 0u, 0u, 0u};
;         if (g.epi == E_MERGEN) pv = *(const u32x4*)op;
; #pragma unroll
;         for (int e = 0; e < 4; ++e) {
;           const float g0 = sigmoid_f(__uint_as_float(gt[e] << 16)), g1 = sigmoid_f(__uint_as_float(gt[e] & 0xffff0000u));
;           const float a0 = __uint_as_float(v[e] << 16), a1 = __uint_as_float(v[e] & 0xffff0000u);
;           const float p0 = __uint_as_float(pv[e] << 16), p1 = __uint_as_float(pv[e] & 0xffff0000u);
;           v[e] = pack2(p0 + g0 * a0, p1 + g1 * a1);
;         }
;       }
;       *(u32x4*)op = v;
.LBB0_962:
	s_cmp_lg_u32 s56, 0
	s_cselect_b32 s58, s26, 0x2880
	s_ashr_i32 s25, s24, 31
	s_lshl_b64 s[26:27], s[24:25], 1
	s_add_u32 s26, s0, s26
	s_addc_u32 s27, s1, s27
	s_and_b32 s0, s56, 14
	s_cmp_lg_u32 s0, 6
	s_cselect_b64 s[28:29], -1, 0
	s_cmp_eq_u32 s56, 7
	s_cselect_b64 s[34:35], -1, 0
	s_lshl_b32 s0, s2, 1
	s_add_u32 s52, s84, s0
	v_cvt_pk_bf16_f32 v2, v6, v7
	v_cvt_pk_bf16_f32 v3, v8, v9
	s_mov_b32 s57, 0
	s_addc_u32 s53, s85, 0
	ds_write2_b64 v0, v[10:11], v[2:3] offset0:8 offset1:12
	s_waitcnt lgkmcnt(0)
	s_barrier
	s_andn2_b64 vcc, exec, s[28:29]
	s_cbranch_vccz .Lmy_plain
	s_and_b64 vcc, exec, s[34:35]
	s_cbranch_vccnz .Lmy_mergeN
.Lmy_merge0:
	v_lshrrev_b32_e32 v2, 5, v224
	v_and_b32_e32 v3, 31, v224
	v_lshlrev_b32_e32 v3, 4, v3
	v_mul_u32_u24_e32 v18, 0x210, v2
	v_add_u32_e32 v18, v18, v3
	v_add_u32_e32 v2, s23, v2
	v_mul_lo_u32 v160, v2, s48
	v_add_u32_e32 v160, v160, v3
	v_lshl_add_u32 v19, v2, 12, v3
	s_lshl_b32 s0, s24, 1
	s_add_u32 s60, s52, s0
	s_addc_u32 s61, s53, 0
	s_add_u32 s60, s60, 0x7cf6800
	s_addc_u32 s61, s61, 0
	s_mov_b64 s[62:63], s[26:27]
	s_mov_b64 s[64:65], s[26:27]
	v_mov_b32_e32 v16, 0
	v_mov_b32_e32 v17, 0
	global_load_dwordx4 v[186:189], v160, s[60:61]
	s_add_u32 s60, s60, 0x51000
	s_addc_u32 s61, s61, 0
	global_load_dwordx4 v[190:193], v160, s[60:61]
	s_add_u32 s60, s60, 0x51000
	s_addc_u32 s61, s61, 0
	global_load_dwordx4 v[194:197], v160, s[60:61]
	s_add_u32 s60, s60, 0x51000
	s_addc_u32 s61, s61, 0
	global_load_dwordx4 v[198:201], v160, s[60:61]
	s_add_u32 s60, s60, 0x51000
	s_addc_u32 s61, s61, 0
	s_mov_b32 s57, 0
.Lmy_merge0_loop:
	ds_read_b128 v[148:151], v18
	v_add_u32_e32 v18, 0x2100, v18
	s_waitcnt vmcnt(3)
	v_lshlrev_b32_e32 v2, 16, v186
	v_and_b32_e32 v3, 0xffff0000, v186
	v_mul_f32_e32 v2, 0xbfb8aa3b, v2
	v_mul_f32_e32 v3, 0xbfb8aa3b, v3
	v_exp_f32_e32 v2, v2
	v_exp_f32_e32 v3, v3
	v_add_f32_e32 v2, 1.0, v2
	v_add_f32_e32 v3, 1.0, v3
	v_div_scale_f32 v5, s[30:31], v3, v3, 1.0
	v_div_scale_f32 v4, s[30:31], v2, v2, 1.0
	v_rcp_f32_e32 v7, v5
	v_rcp_f32_e32 v6, v4
	v_fma_f32 v9, -v5, v7, 1.0
	v_fma_f32 v8, -v4, v6, 1.0
	v_fmac_f32_e32 v7, v9, v7
	v_fmac_f32_e32 v6, v8, v6
	v_div_scale_f32 v9, vcc, 1.0, v3, 1.0
	v_mul_f32_e32 v11, v9, v7
	v_fma_f32 v13, -v5, v11, v9
	v_fmac_f32_e32 v11, v13, v7
	v_fma_f32 v5, -v5, v11, v9
	v_div_fmas_f32 v5, v5, v7, v11
	v_div_fixup_f32 v3, v5, v3, 1.0
	v_div_scale_f32 v8, vcc, 1.0, v2, 1.0
	v_mul_f32_e32 v10, v8, v6
	v_fma_f32 v12, -v4, v10, v8
	v_fmac_f32_e32 v10, v12, v6
	v_fma_f32 v4, -v4, v10, v8
	v_div_fmas_f32 v4, v4, v6, v10
	v_div_fixup_f32 v2, v4, v2, 1.0
	s_waitcnt lgkmcnt(0)
	v_lshlrev_b32_e32 v14, 16, v148
	v_and_b32_e32 v15, 0xffff0000, v148
	v_fma_f32 v2, v2, v14, v16
	v_fma_f32 v3, v3, v15, v17
	v_cvt_pk_bf16_f32 v156, v2, v3
	v_lshlrev_b32_e32 v2, 16, v187
	v_and_b32_e32 v3, 0xffff0000, v187
	v_mul_f32_e32 v2, 0xbfb8aa3b, v2
	v_mul_f32_e32 v3, 0xbfb8aa3b, v3
	v_exp_f32_e32 v2, v2
	v_exp_f32_e32 v3, v3
	v_add_f32_e32 v2, 1.0, v2
	v_add_f32_e32 v3, 1.0, v3
	v_div_scale_f32 v5, s[30:31], v3, v3, 1.0
	v_div_scale_f32 v4, s[30:31], v2, v2, 1.0
	v_rcp_f32_e32 v7, v5
	v_rcp_f32_e32 v6, v4
	v_fma_f32 v9, -v5, v7, 1.0
	v_fma_f32 v8, -v4, v6, 1.0
	v_fmac_f32_e32 v7, v9, v7
	v_fmac_f32_e32 v6, v8, v6
	v_div_scale_f32 v9, vcc, 1.0, v3, 1.0
	v_mul_f32_e32 v11, v9, v7
	v_fma_f32 v13, -v5, v11, v9
	v_fmac_f32_e32 v11, v13, v7
	v_fma_f32 v5, -v5, v11, v9
	v_div_fmas_f32 v5, v5, v7, v11
	v_div_fixup_f32 v3, v5, v3, 1.0
	v_div_scale_f32 v8, vcc, 1.0, v2, 1.0
	v_mul_f32_e32 v10, v8, v6
	v_fma_f32 v12, -v4, v10, v8
	v_fmac_f32_e32 v10, v12, v6
	v_fma_f32 v4, -v4, v10, v8
	v_div_fmas_f32 v4, v4, v6, v10
	v_div_fixup_f32 v2, v4, v2, 1.0
	v_lshlrev_b32_e32 v14, 16, v149
	v_and_b32_e32 v15, 0xffff0000, v149
	v_fma_f32 v2, v2, v14, v16
	v_fma_f32 v3, v3, v15, v17
	v_cvt_pk_bf16_f32 v157, v2, v3
	v_lshlrev_b32_e32 v2, 16, v188
	v_and_b32_e32 v3, 0xffff0000, v188
	v_mul_f32_e32 v2, 0xbfb8aa3b, v2
	v_mul_f32_e32 v3, 0xbfb8aa3b, v3
	v_exp_f32_e32 v2, v2
	v_exp_f32_e32 v3, v3
	v_add_f32_e32 v2, 1.0, v2
	v_add_f32_e32 v3, 1.0, v3
	v_div_scale_f32 v5, s[30:31], v3, v3, 1.0
	v_div_scale_f32 v4, s[30:31], v2, v2, 1.0
	v_rcp_f32_e32 v7, v5
	v_rcp_f32_e32 v6, v4
	v_fma_f32 v9, -v5, v7, 1.0
	v_fma_f32 v8, -v4, v6, 1.0
	v_fmac_f32_e32 v7, v9, v7
	v_fmac_f32_e32 v6, v8, v6
	v_div_scale_f32 v9, vcc, 1.0, v3, 1.0
	v_mul_f32_e32 v11, v9, v7
	v_fma_f32 v13, -v5, v11, v9
	v_fmac_f32_e32 v11, v13, v7
	v_fma_f32 v5, -v5, v11, v9
	v_div_fmas_f32 v5, v5, v7, v11
	v_div_fixup_f32 v3, v5, v3, 1.0
	v_div_scale_f32 v8, vcc, 1.0, v2, 1.0
	v_mul_f32_e32 v10, v8, v6
	v_fma_f32 v12, -v4, v10, v8
	v_fmac_f32_e32 v10, v12, v6
	v_fma_f32 v4, -v4, v10, v8
	v_div_fmas_f32 v4, v4, v6, v10
	v_div_fixup_f32 v2, v4, v2, 1.0
	v_lshlrev_b32_e32 v14, 16, v150
	v_and_b32_e32 v15, 0xffff0000, v150
	v_fma_f32 v2, v2, v14, v16
	v_fma_f32 v3, v3, v15, v17
	v_cvt_pk_bf16_f32 v158, v2, v3
	v_lshlrev_b32_e32 v2, 16, v189
	v_and_b32_e32 v3, 0xffff0000, v189
	v_mul_f32_e32 v2, 0xbfb8aa3b, v2
	v_mul_f32_e32 v3, 0xbfb8aa3b, v3
	v_exp_f32_e32 v2, v2
	v_exp_f32_e32 v3, v3
	v_add_f32_e32 v2, 1.0, v2
	v_add_f32_e32 v3, 1.0, v3
	v_div_scale_f32 v5, s[30:31], v3, v3, 1.0
	v_div_scale_f32 v4, s[30:31], v2, v2, 1.0
	v_rcp_f32_e32 v7, v5
	v_rcp_f32_e32 v6, v4
	v_fma_f32 v9, -v5, v7, 1.0
	v_fma_f32 v8, -v4, v6, 1.0
	v_fmac_f32_e32 v7, v9, v7
	v_fmac_f32_e32 v6, v8, v6
	v_div_scale_f32 v9, vcc, 1.0, v3, 1.0
	v_mul_f32_e32 v11, v9, v7
	v_fma_f32 v13, -v5, v11, v9
	v_fmac_f32_e32 v11, v13, v7
	v_fma_f32 v5, -v5, v11, v9
	v_div_fmas_f32 v5, v5, v7, v11
	v_div_fixup_f32 v3, v5, v3, 1.0
	v_div_scale_f32 v8, vcc, 1.0, v2, 1.0
	v_mul_f32_e32 v10, v8, v6
	v_fma_f32 v12, -v4, v10, v8
	v_fmac_f32_e32 v10, v12, v6
	v_fma_f32 v4, -v4, v10, v8
	v_div_fmas_f32 v4, v4, v6, v10
	v_div_fixup_f32 v2, v4, v2, 1.0
	v_lshlrev_b32_e32 v14, 16, v151
	v_and_b32_e32 v15, 0xffff0000, v151
	v_fma_f32 v2, v2, v14, v16
	v_fma_f32 v3, v3, v15, v17
	v_cvt_pk_bf16_f32 v159, v2, v3
	global_load_dwordx4 v[186:189], v160, s[60:61]
	s_add_u32 s60, s60, 0x51000
	s_addc_u32 s61, s61, 0
	global_store_dwordx4 v19, v[156:159], s[64:65]
	s_add_u32 s64, s64, 0x10000
	s_addc_u32 s65, s65, 0
	ds_read_b128 v[148:151], v18
	v_add_u32_e32 v18, 0x2100, v18
	s_waitcnt vmcnt(4)
; __device__ __forceinline__ float sigmoid_f(float x) { return 1.f / (1.f + __expf(-x)); }
; template <int NT, int BM, int BN, bool PLAIN, int NSTAGE, bool EPI_LDS>
; __device__ __forceinline__ void gemm_tile(const Params& p, const GemmDesc& g, bf16_t* lds, const int tid) {
;     ...
;     for (int i = 0; i < NIT; ++i) {
;       const int id = tid + NT * i;
;       const int row = id / PPR, pc = id % PPR;
;       u32x4 v = *(const u32x4*)(ct + row * CST + pc * 8);
;       bf16_t* op = o + (long)(m0e + row) * ldo + n0e + pc * 8;
;       if (g.epi == E_MERGE0 || g.epi == E_MERGEN) {
;         const u32x4 gt = *(const u32x4*)(((bf16_t*)(p.ws + OFF_proj)) + (long)(m0e + row) * LDP + gcol + n0e + pc * 8);
;         u32x4 pv = u32x4{0u, 0u, 0u, 0u};
;         if (g.epi == E_MERGEN) pv = *(const u32x4*)op;
; #pragma unroll
;         for (int e = 0; e < 4; ++e) {
;           const float g0 = sigmoid_f(__uint_as_float(gt[e] << 16)), g1 = sigmoid_f(__uint_as_float(gt[e] & 0xffff0000u));
;           const float a0 = __uint_as_float(v[e] << 16), a1 = __uint_as_float(v[e] & 0xffff0000u);
;           const float p0 = __uint_as_float(pv[e] << 16), p1 = __uint_as_float(pv[e] & 0xffff0000u);
;           v[e] = pack2(p0 + g0 * a0, p1 + g1 * a1);
;         }
;       }
;       *(u32x4*)op = v;
	v_lshlrev_b32_e32 v2, 16, v190
	v_and_b32_e32 v3, 0xffff0000, v190
	v_mul_f32_e32 v2, 0xbfb8aa3b, v2
	v_mul_f32_e32 v3, 0xbfb8aa3b, v3
	v_exp_f32_e32 v2, v2
	v_exp_f32_e32 v3, v3
	v_add_f32_e32 v2, 1.0, v2
	v_add_f32_e32 v3, 1.0, v3
	v_div_scale_f32 v5, s[30:31], v3, v3, 1.0
	v_div_scale_f32 v4, s[30:31], v2, v2, 1.0
	v_rcp_f32_e32 v7, v5
	v_rcp_f32_e32 v6, v4
	v_fma_f32 v9, -v5, v7, 1.0
	v_fma_f32 v8, -v4, v6, 1.0
	v_fmac_f32_e32 v7, v9, v7
	v_fmac_f32_e32 v6, v8, v6
	v_div_scale_f32 v9, vcc, 1.0, v3, 1.0
	v_mul_f32_e32 v11, v9, v7
	v_fma_f32 v13, -v5, v11, v9
	v_fmac_f32_e32 v11, v13, v7
	v_fma_f32 v5, -v5, v11, v9
	v_div_fmas_f32 v5, v5, v7, v11
	v_div_fixup_f32 v3, v5, v3, 1.0
	v_div_scale_f32 v8, vcc, 1.0, v2, 1.0
	v_mul_f32_e32 v10, v8, v6
	v_fma_f32 v12, -v4, v10, v8
	v_fmac_f32_e32 v10, v12, v6
	v_fma_f32 v4, -v4, v10, v8
	v_div_fmas_f32 v4, v4, v6, v10
	v_div_fixup_f32 v2, v4, v2, 1.0
	s_waitcnt lgkmcnt(0)
	v_lshlrev_b32_e32 v14, 16, v148
	v_and_b32_e32 v15, 0xffff0000, v148
	v_fma_f32 v2, v2, v14, v16
	v_fma_f32 v3, v3, v15, v17
	v_cvt_pk_bf16_f32 v156, v2, v3
	v_lshlrev_b32_e32 v2, 16, v191
	v_and_b32_e32 v3, 0xffff0000, v191
	v_mul_f32_e32 v2, 0xbfb8aa3b, v2
	v_mul_f32_e32 v3, 0xbfb8aa3b, v3
	v_exp_f32_e32 v2, v2
	v_exp_f32_e32 v3, v3
	v_add_f32_e32 v2, 1.0, v2
	v_add_f32_e32 v3, 1.0, v3
	v_div_scale_f32 v5, s[30:31], v3, v3, 1.0
	v_div_scale_f32 v4, s[30:31], v2, v2, 1.0
	v_rcp_f32_e32 v7, v5
	v_rcp_f32_e32 v6, v4
	v_fma_f32 v9, -v5, v7, 1.0
	v_fma_f32 v8, -v4, v6, 1.0
	v_fmac_f32_e32 v7, v9, v7
	v_fmac_f32_e32 v6, v8, v6
	v_div_scale_f32 v9, vcc, 1.0, v3, 1.0
	v_mul_f32_e32 v11, v9, v7
	v_fma_f32 v13, -v5, v11, v9
	v_fmac_f32_e32 v11, v13, v7
	v_fma_f32 v5, -v5, v11, v9
	v_div_fmas_f32 v5, v5, v7, v11
	v_div_fixup_f32 v3, v5, v3, 1.0
	v_div_scale_f32 v8, vcc, 1.0, v2, 1.0
	v_mul_f32_e32 v10, v8, v6
	v_fma_f32 v12, -v4, v10, v8
	v_fmac_f32_e32 v10, v12, v6
	v_fma_f32 v4, -v4, v10, v8
	v_div_fmas_f32 v4, v4, v6, v10
	v_div_fixup_f32 v2, v4, v2, 1.0
	v_lshlrev_b32_e32 v14, 16, v149
	v_and_b32_e32 v15, 0xffff0000, v149
	v_fma_f32 v2, v2, v14, v16
	v_fma_f32 v3, v3, v15, v17
	v_cvt_pk_bf16_f32 v157, v2, v3
	v_lshlrev_b32_e32 v2, 16, v192
	v_and_b32_e32 v3, 0xffff0000, v192
	v_mul_f32_e32 v2, 0xbfb8aa3b, v2
	v_mul_f32_e32 v3, 0xbfb8aa3b, v3
	v_exp_f32_e32 v2, v2
	v_exp_f32_e32 v3, v3
	v_add_f32_e32 v2, 1.0, v2
	v_add_f32_e32 v3, 1.0, v3
	v_div_scale_f32 v5, s[30:31], v3, v3, 1.0
	v_div_scale_f32 v4, s[30:31], v2, v2, 1.0
	v_rcp_f32_e32 v7, v5
	v_rcp_f32_e32 v6, v4
	v_fma_f32 v9, -v5, v7, 1.0
	v_fma_f32 v8, -v4, v6, 1.0
	v_fmac_f32_e32 v7, v9, v7
	v_fmac_f32_e32 v6, v8, v6
	v_div_scale_f32 v9, vcc, 1.0, v3, 1.0
	v_mul_f32_e32 v11, v9, v7
	v_fma_f32 v13, -v5, v11, v9
	v_fmac_f32_e32 v11, v13, v7
	v_fma_f32 v5, -v5, v11, v9
	v_div_fmas_f32 v5, v5, v7, v11
	v_div_fixup_f32 v3, v5, v3, 1.0
	v_div_scale_f32 v8, vcc, 1.0, v2, 1.0
	v_mul_f32_e32 v10, v8, v6
	v_fma_f32 v12, -v4, v10, v8
	v_fmac_f32_e32 v10, v12, v6
	v_fma_f32 v4, -v4, v10, v8
	v_div_fmas_f32 v4, v4, v6, v10
	v_div_fixup_f32 v2, v4, v2, 1.0
	v_lshlrev_b32_e32 v14, 16, v150
	v_and_b32_e32 v15, 0xffff0000, v150
	v_fma_f32 v2, v2, v14, v16
	v_fma_f32 v3, v3, v15, v17
	v_cvt_pk_bf16_f32 v158, v2, v3
	v_lshlrev_b32_e32 v2, 16, v193
	v_and_b32_e32 v3, 0xffff0000, v193
	v_mul_f32_e32 v2, 0xbfb8aa3b, v2
	v_mul_f32_e32 v3, 0xbfb8aa3b, v3
	v_exp_f32_e32 v2, v2
	v_exp_f32_e32 v3, v3
	v_add_f32_e32 v2, 1.0, v2
	v_add_f32_e32 v3, 1.0, v3
	v_div_scale_f32 v5, s[30:31], v3, v3, 1.0
	v_div_scale_f32 v4, s[30:31], v2, v2, 1.0
	v_rcp_f32_e32 v7, v5
	v_rcp_f32_e32 v6, v4
	v_fma_f32 v9, -v5, v7, 1.0
	v_fma_f32 v8, -v4, v6, 1.0
	v_fmac_f32_e32 v7, v9, v7
	v_fmac_f32_e32 v6, v8, v6
	v_div_scale_f32 v9, vcc, 1.0, v3, 1.0
	v_mul_f32_e32 v11, v9, v7
	v_fma_f32 v13, -v5, v11, v9
	v_fmac_f32_e32 v11, v13, v7
	v_fma_f32 v5, -v5, v11, v9
	v_div_fmas_f32 v5, v5, v7, v11
	v_div_fixup_f32 v3, v5, v3, 1.0
	v_div_scale_f32 v8, vcc, 1.0, v2, 1.0
	v_mul_f32_e32 v10, v8, v6
	v_fma_f32 v12, -v4, v10, v8
	v_fmac_f32_e32 v10, v12, v6
	v_fma_f32 v4, -v4, v10, v8
	v_div_fmas_f32 v4, v4, v6, v10
	v_div_fixup_f32 v2, v4, v2, 1.0
	v_lshlrev_b32_e32 v14, 16, v151
	v_and_b32_e32 v15, 0xffff0000, v151
	v_fma_f32 v2, v2, v14, v16
	v_fma_f32 v3, v3, v15, v17
	v_cvt_pk_bf16_f32 v159, v2, v3
	global_load_dwordx4 v[190:193], v160, s[60:61]
	s_add_u32 s60, s60, 0x51000
	s_addc_u32 s61, s61, 0
	global_store_dwordx4 v19, v[156:159], s[64:65]
	s_add_u32 s64, s64, 0x10000
	s_addc_u32 s65, s65, 0
	ds_read_b128 v[148:151], v18
	v_add_u32_e32 v18, 0x2100, v18
	s_waitcnt vmcnt(5)
	v_lshlrev_b32_e32 v2, 16, v194
	v_and_b32_e32 v3, 0xffff0000, v194
	v_mul_f32_e32 v2, 0xbfb8aa3b, v2
	v_mul_f32_e32 v3, 0xbfb8aa3b, v3
	v_exp_f32_e32 v2, v2
	v_exp_f32_e32 v3, v3
	v_add_f32_e32 v2, 1.0, v2
	v_add_f32_e32 v3, 1.0, v3
	v_div_scale_f32 v5, s[30:31], v3, v3, 1.0
	v_div_scale_f32 v4, s[30:31], v2, v2, 1.0
	v_rcp_f32_e32 v7, v5
	v_rcp_f32_e32 v6, v4
	v_fma_f32 v9, -v5, v7, 1.0
	v_fma_f32 v8, -v4, v6, 1.0
	v_fmac_f32_e32 v7, v9, v7
	v_fmac_f32_e32 v6, v8, v6
	v_div_scale_f32 v9, vcc, 1.0, v3, 1.0
	v_mul_f32_e32 v11, v9, v7
	v_fma_f32 v13, -v5, v11, v9
	v_fmac_f32_e32 v11, v13, v7
	v_fma_f32 v5, -v5, v11, v9
	v_div_fmas_f32 v5, v5, v7, v11
	v_div_fixup_f32 v3, v5, v3, 1.0
	v_div_scale_f32 v8, vcc, 1.0, v2, 1.0
	v_mul_f32_e32 v10, v8, v6
	v_fma_f32 v12, -v4, v10, v8
	v_fmac_f32_e32 v10, v12, v6
	v_fma_f32 v4, -v4, v10, v8
	v_div_fmas_f32 v4, v4, v6, v10
	v_div_fixup_f32 v2, v4, v2, 1.0
	s_waitcnt lgkmcnt(0)
; __device__ __forceinline__ float sigmoid_f(float x) { return 1.f / (1.f + __expf(-x)); }
; template <int NT, int BM, int BN, bool PLAIN, int NSTAGE, bool EPI_LDS>
; __device__ __forceinline__ void gemm_tile(const Params& p, const GemmDesc& g, bf16_t* lds, const int tid) {
;     ...
;     for (int i = 0; i < NIT; ++i) {
;       const int id = tid + NT * i;
;       const int row = id / PPR, pc = id % PPR;
;       u32x4 v = *(const u32x4*)(ct + row * CST + pc * 8);
;       bf16_t* op = o + (long)(m0e + row) * ldo + n0e + pc * 8;
;       if (g.epi == E_MERGE0 || g.epi == E_MERGEN) {
;         const u32x4 gt = *(const u32x4*)(((bf16_t*)(p.ws + OFF_proj)) + (long)(m0e + row) * LDP + gcol + n0e + pc * 8);
;         u32x4 pv = u32x4{0u, 0u, 0u, 0u};
;         if (g.epi == E_MERGEN) pv = *(const u32x4*)op;
; #pragma unroll
;         for (int e = 0; e < 4; ++e) {
;           const float g0 = sigmoid_f(__uint_as_float(gt[e] << 16)), g1 = sigmoid_f(__uint_as_float(gt[e] & 0xffff0000u));
;           const float a0 = __uint_as_float(v[e] << 16), a1 = __uint_as_float(v[e] & 0xffff0000u);
;           const float p0 = __uint_as_float(pv[e] << 16), p1 = __uint_as_float(pv[e] & 0xffff0000u);
;           v[e] = pack2(p0 + g0 * a0, p1 + g1 * a1);
;         }
;       }
;       *(u32x4*)op = v;
	v_lshlrev_b32_e32 v14, 16, v148
	v_and_b32_e32 v15, 0xffff0000, v148
	v_fma_f32 v2, v2, v14, v16
	v_fma_f32 v3, v3, v15, v17
	v_cvt_pk_bf16_f32 v156, v2, v3
	v_lshlrev_b32_e32 v2, 16, v195
	v_and_b32_e32 v3, 0xffff0000, v195
	v_mul_f32_e32 v2, 0xbfb8aa3b, v2
	v_mul_f32_e32 v3, 0xbfb8aa3b, v3
	v_exp_f32_e32 v2, v2
	v_exp_f32_e32 v3, v3
	v_add_f32_e32 v2, 1.0, v2
	v_add_f32_e32 v3, 1.0, v3
	v_div_scale_f32 v5, s[30:31], v3, v3, 1.0
	v_div_scale_f32 v4, s[30:31], v2, v2, 1.0
	v_rcp_f32_e32 v7, v5
	v_rcp_f32_e32 v6, v4
	v_fma_f32 v9, -v5, v7, 1.0
	v_fma_f32 v8, -v4, v6, 1.0
	v_fmac_f32_e32 v7, v9, v7
	v_fmac_f32_e32 v6, v8, v6
	v_div_scale_f32 v9, vcc, 1.0, v3, 1.0
	v_mul_f32_e32 v11, v9, v7
	v_fma_f32 v13, -v5, v11, v9
	v_fmac_f32_e32 v11, v13, v7
	v_fma_f32 v5, -v5, v11, v9
	v_div_fmas_f32 v5, v5, v7, v11
	v_div_fixup_f32 v3, v5, v3, 1.0
	v_div_scale_f32 v8, vcc, 1.0, v2, 1.0
	v_mul_f32_e32 v10, v8, v6
	v_fma_f32 v12, -v4, v10, v8
	v_fmac_f32_e32 v10, v12, v6
	v_fma_f32 v4, -v4, v10, v8
	v_div_fmas_f32 v4, v4, v6, v10
	v_div_fixup_f32 v2, v4, v2, 1.0
	v_lshlrev_b32_e32 v14, 16, v149
	v_and_b32_e32 v15, 0xffff0000, v149
	v_fma_f32 v2, v2, v14, v16
	v_fma_f32 v3, v3, v15, v17
	v_cvt_pk_bf16_f32 v157, v2, v3
	v_lshlrev_b32_e32 v2, 16, v196
	v_and_b32_e32 v3, 0xffff0000, v196
	v_mul_f32_e32 v2, 0xbfb8aa3b, v2
	v_mul_f32_e32 v3, 0xbfb8aa3b, v3
	v_exp_f32_e32 v2, v2
	v_exp_f32_e32 v3, v3
	v_add_f32_e32 v2, 1.0, v2
	v_add_f32_e32 v3, 1.0, v3
	v_div_scale_f32 v5, s[30:31], v3, v3, 1.0
	v_div_scale_f32 v4, s[30:31], v2, v2, 1.0
	v_rcp_f32_e32 v7, v5
	v_rcp_f32_e32 v6, v4
	v_fma_f32 v9, -v5, v7, 1.0
	v_fma_f32 v8, -v4, v6, 1.0
	v_fmac_f32_e32 v7, v9, v7
	v_fmac_f32_e32 v6, v8, v6
	v_div_scale_f32 v9, vcc, 1.0, v3, 1.0
	v_mul_f32_e32 v11, v9, v7
	v_fma_f32 v13, -v5, v11, v9
	v_fmac_f32_e32 v11, v13, v7
	v_fma_f32 v5, -v5, v11, v9
	v_div_fmas_f32 v5, v5, v7, v11
	v_div_fixup_f32 v3, v5, v3, 1.0
	v_div_scale_f32 v8, vcc, 1.0, v2, 1.0
	v_mul_f32_e32 v10, v8, v6
	v_fma_f32 v12, -v4, v10, v8
	v_fmac_f32_e32 v10, v12, v6
	v_fma_f32 v4, -v4, v10, v8
	v_div_fmas_f32 v4, v4, v6, v10
	v_div_fixup_f32 v2, v4, v2, 1.0
	v_lshlrev_b32_e32 v14, 16, v150
	v_and_b32_e32 v15, 0xffff0000, v150
	v_fma_f32 v2, v2, v14, v16
	v_fma_f32 v3, v3, v15, v17
	v_cvt_pk_bf16_f32 v158, v2, v3
	v_lshlrev_b32_e32 v2, 16, v197
	v_and_b32_e32 v3, 0xffff0000, v197
	v_mul_f32_e32 v2, 0xbfb8aa3b, v2
	v_mul_f32_e32 v3, 0xbfb8aa3b, v3
	v_exp_f32_e32 v2, v2
	v_exp_f32_e32 v3, v3
	v_add_f32_e32 v2, 1.0, v2
	v_add_f32_e32 v3, 1.0, v3
	v_div_scale_f32 v5, s[30:31], v3, v3, 1.0
	v_div_scale_f32 v4, s[30:31], v2, v2, 1.0
	v_rcp_f32_e32 v7, v5
	v_rcp_f32_e32 v6, v4
	v_fma_f32 v9, -v5, v7, 1.0
	v_fma_f32 v8, -v4, v6, 1.0
	v_fmac_f32_e32 v7, v9, v7
	v_fmac_f32_e32 v6, v8, v6
	v_div_scale_f32 v9, vcc, 1.0, v3, 1.0
	v_mul_f32_e32 v11, v9, v7
	v_fma_f32 v13, -v5, v11, v9
	v_fmac_f32_e32 v11, v13, v7
	v_fma_f32 v5, -v5, v11, v9
	v_div_fmas_f32 v5, v5, v7, v11
	v_div_fixup_f32 v3, v5, v3, 1.0
	v_div_scale_f32 v8, vcc, 1.0, v2, 1.0
	v_mul_f32_e32 v10, v8, v6
	v_fma_f32 v12, -v4, v10, v8
	v_fmac_f32_e32 v10, v12, v6
	v_fma_f32 v4, -v4, v10, v8
	v_div_fmas_f32 v4, v4, v6, v10
	v_div_fixup_f32 v2, v4, v2, 1.0
	v_lshlrev_b32_e32 v14, 16, v151
	v_and_b32_e32 v15, 0xffff0000, v151
	v_fma_f32 v2, v2, v14, v16
	v_fma_f32 v3, v3, v15, v17
	v_cvt_pk_bf16_f32 v159, v2, v3
	global_load_dwordx4 v[194:197], v160, s[60:61]
	s_add_u32 s60, s60, 0x51000
	s_addc_u32 s61, s61, 0
	global_store_dwordx4 v19, v[156:159], s[64:65]
	s_add_u32 s64, s64, 0x10000
	s_addc_u32 s65, s65, 0
	ds_read_b128 v[148:151], v18
	v_add_u32_e32 v18, 0x2100, v18
	s_waitcnt vmcnt(6)
	v_lshlrev_b32_e32 v2, 16, v198
	v_and_b32_e32 v3, 0xffff0000, v198
	v_mul_f32_e32 v2, 0xbfb8aa3b, v2
	v_mul_f32_e32 v3, 0xbfb8aa3b, v3
	v_exp_f32_e32 v2, v2
	v_exp_f32_e32 v3, v3
	v_add_f32_e32 v2, 1.0, v2
	v_add_f32_e32 v3, 1.0, v3
	v_div_scale_f32 v5, s[30:31], v3, v3, 1.0
	v_div_scale_f32 v4, s[30:31], v2, v2, 1.0
	v_rcp_f32_e32 v7, v5
	v_rcp_f32_e32 v6, v4
	v_fma_f32 v9, -v5, v7, 1.0
	v_fma_f32 v8, -v4, v6, 1.0
	v_fmac_f32_e32 v7, v9, v7
	v_fmac_f32_e32 v6, v8, v6
	v_div_scale_f32 v9, vcc, 1.0, v3, 1.0
	v_mul_f32_e32 v11, v9, v7
	v_fma_f32 v13, -v5, v11, v9
	v_fmac_f32_e32 v11, v13, v7
	v_fma_f32 v5, -v5, v11, v9
	v_div_fmas_f32 v5, v5, v7, v11
	v_div_fixup_f32 v3, v5, v3, 1.0
	v_div_scale_f32 v8, vcc, 1.0, v2, 1.0
	v_mul_f32_e32 v10, v8, v6
	v_fma_f32 v12, -v4, v10, v8
	v_fmac_f32_e32 v10, v12, v6
	v_fma_f32 v4, -v4, v10, v8
	v_div_fmas_f32 v4, v4, v6, v10
	v_div_fixup_f32 v2, v4, v2, 1.0
	s_waitcnt lgkmcnt(0)
; __device__ __forceinline__ float sigmoid_f(float x) { return 1.f / (1.f + __expf(-x)); }
; template <int NT, int BM, int BN, bool PLAIN, int NSTAGE, bool EPI_LDS>
; __device__ __forceinline__ void gemm_tile(const Params& p, const GemmDesc& g, bf16_t* lds, const int tid) {
;     ...
;     for (int i = 0; i < NIT; ++i) {
;       const int id = tid + NT * i;
;       const int row = id / PPR, pc = id % PPR;
;       u32x4 v = *(const u32x4*)(ct + row * CST + pc * 8);
;       bf16_t* op = o + (long)(m0e + row) * ldo + n0e + pc * 8;
;       if (g.epi == E_MERGE0 || g.epi == E_MERGEN) {
;         const u32x4 gt = *(const u32x4*)(((bf16_t*)(p.ws + OFF_proj)) + (long)(m0e + row) * LDP + gcol + n0e + pc * 8);
;         u32x4 pv = u32x4{0u, 0u, 0u, 0u};
;         if (g.epi == E_MERGEN) pv = *(const u32x4*)op;
; #pragma unroll
;         for (int e = 0; e < 4; ++e) {
;           const float g0 = sigmoid_f(__uint_as_float(gt[e] << 16)), g1 = sigmoid_f(__uint_as_float(gt[e] & 0xffff0000u));
;           const float a0 = __uint_as_float(v[e] << 16), a1 = __uint_as_float(v[e] & 0xffff0000u);
;           const float p0 = __uint_as_float(pv[e] << 16), p1 = __uint_as_float(pv[e] & 0xffff0000u);
;           v[e] = pack2(p0 + g0 * a0, p1 + g1 * a1);
;         }
;       }
;       *(u32x4*)op = v;
	v_lshlrev_b32_e32 v14, 16, v148
	v_and_b32_e32 v15, 0xffff0000, v148
	v_fma_f32 v2, v2, v14, v16
	v_fma_f32 v3, v3, v15, v17
	v_cvt_pk_bf16_f32 v156, v2, v3
	v_lshlrev_b32_e32 v2, 16, v199
	v_and_b32_e32 v3, 0xffff0000, v199
	v_mul_f32_e32 v2, 0xbfb8aa3b, v2
	v_mul_f32_e32 v3, 0xbfb8aa3b, v3
	v_exp_f32_e32 v2, v2
	v_exp_f32_e32 v3, v3
	v_add_f32_e32 v2, 1.0, v2
	v_add_f32_e32 v3, 1.0, v3
	v_div_scale_f32 v5, s[30:31], v3, v3, 1.0
	v_div_scale_f32 v4, s[30:31], v2, v2, 1.0
	v_rcp_f32_e32 v7, v5
	v_rcp_f32_e32 v6, v4
	v_fma_f32 v9, -v5, v7, 1.0
	v_fma_f32 v8, -v4, v6, 1.0
	v_fmac_f32_e32 v7, v9, v7
	v_fmac_f32_e32 v6, v8, v6
	v_div_scale_f32 v9, vcc, 1.0, v3, 1.0
	v_mul_f32_e32 v11, v9, v7
	v_fma_f32 v13, -v5, v11, v9
	v_fmac_f32_e32 v11, v13, v7
	v_fma_f32 v5, -v5, v11, v9
	v_div_fmas_f32 v5, v5, v7, v11
	v_div_fixup_f32 v3, v5, v3, 1.0
	v_div_scale_f32 v8, vcc, 1.0, v2, 1.0
	v_mul_f32_e32 v10, v8, v6
	v_fma_f32 v12, -v4, v10, v8
	v_fmac_f32_e32 v10, v12, v6
	v_fma_f32 v4, -v4, v10, v8
	v_div_fmas_f32 v4, v4, v6, v10
	v_div_fixup_f32 v2, v4, v2, 1.0
	v_lshlrev_b32_e32 v14, 16, v149
	v_and_b32_e32 v15, 0xffff0000, v149
	v_fma_f32 v2, v2, v14, v16
	v_fma_f32 v3, v3, v15, v17
	v_cvt_pk_bf16_f32 v157, v2, v3
	v_lshlrev_b32_e32 v2, 16, v200
	v_and_b32_e32 v3, 0xffff0000, v200
	v_mul_f32_e32 v2, 0xbfb8aa3b, v2
	v_mul_f32_e32 v3, 0xbfb8aa3b, v3
	v_exp_f32_e32 v2, v2
	v_exp_f32_e32 v3, v3
	v_add_f32_e32 v2, 1.0, v2
	v_add_f32_e32 v3, 1.0, v3
	v_div_scale_f32 v5, s[30:31], v3, v3, 1.0
	v_div_scale_f32 v4, s[30:31], v2, v2, 1.0
	v_rcp_f32_e32 v7, v5
	v_rcp_f32_e32 v6, v4
	v_fma_f32 v9, -v5, v7, 1.0
	v_fma_f32 v8, -v4, v6, 1.0
	v_fmac_f32_e32 v7, v9, v7
	v_fmac_f32_e32 v6, v8, v6
	v_div_scale_f32 v9, vcc, 1.0, v3, 1.0
	v_mul_f32_e32 v11, v9, v7
	v_fma_f32 v13, -v5, v11, v9
	v_fmac_f32_e32 v11, v13, v7
	v_fma_f32 v5, -v5, v11, v9
	v_div_fmas_f32 v5, v5, v7, v11
	v_div_fixup_f32 v3, v5, v3, 1.0
	v_div_scale_f32 v8, vcc, 1.0, v2, 1.0
	v_mul_f32_e32 v10, v8, v6
	v_fma_f32 v12, -v4, v10, v8
	v_fmac_f32_e32 v10, v12, v6
	v_fma_f32 v4, -v4, v10, v8
	v_div_fmas_f32 v4, v4, v6, v10
	v_div_fixup_f32 v2, v4, v2, 1.0
	v_lshlrev_b32_e32 v14, 16, v150
	v_and_b32_e32 v15, 0xffff0000, v150
	v_fma_f32 v2, v2, v14, v16
	v_fma_f32 v3, v3, v15, v17
	v_cvt_pk_bf16_f32 v158, v2, v3
	v_lshlrev_b32_e32 v2, 16, v201
	v_and_b32_e32 v3, 0xffff0000, v201
	v_mul_f32_e32 v2, 0xbfb8aa3b, v2
	v_mul_f32_e32 v3, 0xbfb8aa3b, v3
	v_exp_f32_e32 v2, v2
	v_exp_f32_e32 v3, v3
	v_add_f32_e32 v2, 1.0, v2
	v_add_f32_e32 v3, 1.0, v3
	v_div_scale_f32 v5, s[30:31], v3, v3, 1.0
	v_div_scale_f32 v4, s[30:31], v2, v2, 1.0
	v_rcp_f32_e32 v7, v5
	v_rcp_f32_e32 v6, v4
	v_fma_f32 v9, -v5, v7, 1.0
	v_fma_f32 v8, -v4, v6, 1.0
	v_fmac_f32_e32 v7, v9, v7
	v_fmac_f32_e32 v6, v8, v6
	v_div_scale_f32 v9, vcc, 1.0, v3, 1.0
	v_mul_f32_e32 v11, v9, v7
	v_fma_f32 v13, -v5, v11, v9
	v_fmac_f32_e32 v11, v13, v7
	v_fma_f32 v5, -v5, v11, v9
	v_div_fmas_f32 v5, v5, v7, v11
	v_div_fixup_f32 v3, v5, v3, 1.0
	v_div_scale_f32 v8, vcc, 1.0, v2, 1.0
	v_mul_f32_e32 v10, v8, v6
	v_fma_f32 v12, -v4, v10, v8
	v_fmac_f32_e32 v10, v12, v6
	v_fma_f32 v4, -v4, v10, v8
	v_div_fmas_f32 v4, v4, v6, v10
	v_div_fixup_f32 v2, v4, v2, 1.0
	v_lshlrev_b32_e32 v14, 16, v151
	v_and_b32_e32 v15, 0xffff0000, v151
	v_fma_f32 v2, v2, v14, v16
	v_fma_f32 v3, v3, v15, v17
	v_cvt_pk_bf16_f32 v159, v2, v3
	global_load_dwordx4 v[198:201], v160, s[60:61]
	s_add_u32 s60, s60, 0x51000
	s_addc_u32 s61, s61, 0
	global_store_dwordx4 v19, v[156:159], s[64:65]
	s_add_u32 s64, s64, 0x10000
	s_addc_u32 s65, s65, 0
	s_add_i32 s57, s57, 1
	s_cmp_eq_u32 s57, 3
	s_cselect_b32 s0, 0x510000, 0
	s_cselect_b32 s2, 0x100000, 0
	s_sub_u32 s60, s60, s0
	s_subb_u32 s61, s61, 0
	s_cmp_lt_u32 s57, 4
	s_cbranch_scc1 .Lmy_merge0_loop
	s_branch .LBB0_888
.Lmy_mergeN:
	v_lshrrev_b32_e32 v2, 5, v224
	v_and_b32_e32 v3, 31, v224
	v_lshlrev_b32_e32 v3, 4, v3
	v_mul_u32_u24_e32 v18, 0x210, v2
	v_add_u32_e32 v18, v18, v3
	v_add_u32_e32 v2, s23, v2
	v_mul_lo_u32 v160, v2, s48
	v_add_u32_e32 v160, v160, v3
	v_lshl_add_u32 v19, v2, 12, v3
	s_lshl_b32 s0, s24, 1
	s_add_u32 s60, s52, s0
	s_addc_u32 s61, s53, 0
	s_add_u32 s60, s60, 0x7cf6800
	s_addc_u32 s61, s61, 0
	s_mov_b64 s[62:63], s[26:27]
	s_mov_b64 s[64:65], s[26:27]
	global_load_dwordx4 v[186:189], v160, s[60:61]
	global_load_dwordx4 v[226:229], v19, s[62:63]
	s_add_u32 s60, s60, 0x51000
	s_addc_u32 s61, s61, 0
	s_add_u32 s62, s62, 0x10000
	s_addc_u32 s63, s63, 0
	global_load_dwordx4 v[190:193], v160, s[60:61]
	global_load_dwordx4 v[230:233], v19, s[62:63]
	s_add_u32 s60, s60, 0x51000
	s_addc_u32 s61, s61, 0
	s_add_u32 s62, s62, 0x10000
	s_addc_u32 s63, s63, 0
	global_load_dwordx4 v[194:197], v160, s[60:61]
	global_load_dwordx4 v[234:237], v19, s[62:63]
	s_add_u32 s60, s60, 0x51000
	s_addc_u32 s61, s61, 0
	s_add_u32 s62, s62, 0x10000
	s_addc_u32 s63, s63, 0
	global_load_dwordx4 v[198:201], v160, s[60:61]
	global_load_dwordx4 v[238:241], v19, s[62:63]
	s_add_u32 s60, s60, 0x51000
	s_addc_u32 s61, s61, 0
	s_add_u32 s62, s62, 0x10000
	s_addc_u32 s63, s63, 0
	s_mov_b32 s57, 0
; __device__ __forceinline__ float sigmoid_f(float x) { return 1.f / (1.f + __expf(-x)); }
; template <int NT, int BM, int BN, bool PLAIN, int NSTAGE, bool EPI_LDS>
; __device__ __forceinline__ void gemm_tile(const Params& p, const GemmDesc& g, bf16_t* lds, const int tid) {
;     ...
;     const long ldo = (g.epi == E_PROJ) ? LDP : (g.epi == E_RELU2 ? 8192 : 2048);
;     const int gcol = COL_BG + g.auxi * 2048;
; #pragma unroll 4
;     for (int i = 0; i < NIT; ++i) {
;       const int id = tid + NT * i;
;       const int row = id / PPR, pc = id % PPR;
;       u32x4 v = *(const u32x4*)(ct + row * CST + pc * 8);
;       bf16_t* op = o + (long)(m0e + row) * ldo + n0e + pc * 8;
;       if (g.epi == E_MERGE0 || g.epi == E_MERGEN) {
;         const u32x4 gt = *(const u32x4*)(((bf16_t*)(p.ws + OFF_proj)) + (long)(m0e + row) * LDP + gcol + n0e + pc * 8);
;         u32x4 pv = u32x4{0u, 0u, 0u, 0u};
;         if (g.epi == E_MERGEN) pv = *(const u32x4*)op;
; #pragma unroll
;         for (int e = 0; e < 4; ++e) {
;           const float g0 = sigmoid_f(__uint_as_float(gt[e] << 16)), g1 = sigmoid_f(__uint_as_float(gt[e] & 0xffff0000u));
;           const float a0 = __uint_as_float(v[e] << 16), a1 = __uint_as_float(v[e] & 0xffff0000u);
;           const float p0 = __uint_as_float(pv[e] << 16), p1 = __uint_as_float(pv[e] & 0xffff0000u);
;           v[e] = pack2(p0 + g0 * a0, p1 + g1 * a1);
;         }
;       }
;       *(u32x4*)op = v;
.Lmy_mergeN_loop:
	ds_read_b128 v[148:151], v18
	v_add_u32_e32 v18, 0x2100, v18
	s_waitcnt vmcnt(6)
	v_lshlrev_b32_e32 v2, 16, v186
	v_and_b32_e32 v3, 0xffff0000, v186
	v_mul_f32_e32 v2, 0xbfb8aa3b, v2
	v_mul_f32_e32 v3, 0xbfb8aa3b, v3
	v_exp_f32_e32 v2, v2
	v_exp_f32_e32 v3, v3
	v_add_f32_e32 v2, 1.0, v2
	v_add_f32_e32 v3, 1.0, v3
	v_div_scale_f32 v5, s[30:31], v3, v3, 1.0
	v_div_scale_f32 v4, s[30:31], v2, v2, 1.0
	v_rcp_f32_e32 v7, v5
	v_rcp_f32_e32 v6, v4
	v_fma_f32 v9, -v5, v7, 1.0
	v_fma_f32 v8, -v4, v6, 1.0
	v_fmac_f32_e32 v7, v9, v7
	v_fmac_f32_e32 v6, v8, v6
	v_div_scale_f32 v9, vcc, 1.0, v3, 1.0
	v_mul_f32_e32 v11, v9, v7
	v_fma_f32 v13, -v5, v11, v9
	v_fmac_f32_e32 v11, v13, v7
	v_fma_f32 v5, -v5, v11, v9
	v_div_fmas_f32 v5, v5, v7, v11
	v_div_fixup_f32 v3, v5, v3, 1.0
	v_div_scale_f32 v8, vcc, 1.0, v2, 1.0
	v_mul_f32_e32 v10, v8, v6
	v_fma_f32 v12, -v4, v10, v8
	v_fmac_f32_e32 v10, v12, v6
	v_fma_f32 v4, -v4, v10, v8
	v_div_fmas_f32 v4, v4, v6, v10
	v_div_fixup_f32 v2, v4, v2, 1.0
	s_waitcnt lgkmcnt(0)
	v_lshlrev_b32_e32 v14, 16, v148
	v_and_b32_e32 v15, 0xffff0000, v148
	v_lshlrev_b32_e32 v16, 16, v226
	v_and_b32_e32 v17, 0xffff0000, v226
	v_fma_f32 v2, v2, v14, v16
	v_fma_f32 v3, v3, v15, v17
	v_cvt_pk_bf16_f32 v156, v2, v3
	v_lshlrev_b32_e32 v2, 16, v187
	v_and_b32_e32 v3, 0xffff0000, v187
	v_mul_f32_e32 v2, 0xbfb8aa3b, v2
	v_mul_f32_e32 v3, 0xbfb8aa3b, v3
	v_exp_f32_e32 v2, v2
	v_exp_f32_e32 v3, v3
	v_add_f32_e32 v2, 1.0, v2
	v_add_f32_e32 v3, 1.0, v3
	v_div_scale_f32 v5, s[30:31], v3, v3, 1.0
	v_div_scale_f32 v4, s[30:31], v2, v2, 1.0
	v_rcp_f32_e32 v7, v5
	v_rcp_f32_e32 v6, v4
	v_fma_f32 v9, -v5, v7, 1.0
	v_fma_f32 v8, -v4, v6, 1.0
	v_fmac_f32_e32 v7, v9, v7
	v_fmac_f32_e32 v6, v8, v6
	v_div_scale_f32 v9, vcc, 1.0, v3, 1.0
	v_mul_f32_e32 v11, v9, v7
	v_fma_f32 v13, -v5, v11, v9
	v_fmac_f32_e32 v11, v13, v7
	v_fma_f32 v5, -v5, v11, v9
	v_div_fmas_f32 v5, v5, v7, v11
	v_div_fixup_f32 v3, v5, v3, 1.0
	v_div_scale_f32 v8, vcc, 1.0, v2, 1.0
	v_mul_f32_e32 v10, v8, v6
	v_fma_f32 v12, -v4, v10, v8
	v_fmac_f32_e32 v10, v12, v6
	v_fma_f32 v4, -v4, v10, v8
	v_div_fmas_f32 v4, v4, v6, v10
	v_div_fixup_f32 v2, v4, v2, 1.0
	v_lshlrev_b32_e32 v14, 16, v149
	v_and_b32_e32 v15, 0xffff0000, v149
	v_lshlrev_b32_e32 v16, 16, v227
	v_and_b32_e32 v17, 0xffff0000, v227
	v_fma_f32 v2, v2, v14, v16
	v_fma_f32 v3, v3, v15, v17
	v_cvt_pk_bf16_f32 v157, v2, v3
	v_lshlrev_b32_e32 v2, 16, v188
	v_and_b32_e32 v3, 0xffff0000, v188
	v_mul_f32_e32 v2, 0xbfb8aa3b, v2
	v_mul_f32_e32 v3, 0xbfb8aa3b, v3
	v_exp_f32_e32 v2, v2
	v_exp_f32_e32 v3, v3
	v_add_f32_e32 v2, 1.0, v2
	v_add_f32_e32 v3, 1.0, v3
	v_div_scale_f32 v5, s[30:31], v3, v3, 1.0
	v_div_scale_f32 v4, s[30:31], v2, v2, 1.0
	v_rcp_f32_e32 v7, v5
	v_rcp_f32_e32 v6, v4
	v_fma_f32 v9, -v5, v7, 1.0
	v_fma_f32 v8, -v4, v6, 1.0
	v_fmac_f32_e32 v7, v9, v7
	v_fmac_f32_e32 v6, v8, v6
	v_div_scale_f32 v9, vcc, 1.0, v3, 1.0
	v_mul_f32_e32 v11, v9, v7
	v_fma_f32 v13, -v5, v11, v9
	v_fmac_f32_e32 v11, v13, v7
	v_fma_f32 v5, -v5, v11, v9
	v_div_fmas_f32 v5, v5, v7, v11
	v_div_fixup_f32 v3, v5, v3, 1.0
	v_div_scale_f32 v8, vcc, 1.0, v2, 1.0
	v_mul_f32_e32 v10, v8, v6
	v_fma_f32 v12, -v4, v10, v8
	v_fmac_f32_e32 v10, v12, v6
	v_fma_f32 v4, -v4, v10, v8
	v_div_fmas_f32 v4, v4, v6, v10
	v_div_fixup_f32 v2, v4, v2, 1.0
	v_lshlrev_b32_e32 v14, 16, v150
	v_and_b32_e32 v15, 0xffff0000, v150
	v_lshlrev_b32_e32 v16, 16, v228
	v_and_b32_e32 v17, 0xffff0000, v228
	v_fma_f32 v2, v2, v14, v16
	v_fma_f32 v3, v3, v15, v17
	v_cvt_pk_bf16_f32 v158, v2, v3
	v_lshlrev_b32_e32 v2, 16, v189
	v_and_b32_e32 v3, 0xffff0000, v189
	v_mul_f32_e32 v2, 0xbfb8aa3b, v2
	v_mul_f32_e32 v3, 0xbfb8aa3b, v3
	v_exp_f32_e32 v2, v2
	v_exp_f32_e32 v3, v3
	v_add_f32_e32 v2, 1.0, v2
	v_add_f32_e32 v3, 1.0, v3
	v_div_scale_f32 v5, s[30:31], v3, v3, 1.0
	v_div_scale_f32 v4, s[30:31], v2, v2, 1.0
	v_rcp_f32_e32 v7, v5
	v_rcp_f32_e32 v6, v4
	v_fma_f32 v9, -v5, v7, 1.0
	v_fma_f32 v8, -v4, v6, 1.0
	v_fmac_f32_e32 v7, v9, v7
	v_fmac_f32_e32 v6, v8, v6
	v_div_scale_f32 v9, vcc, 1.0, v3, 1.0
	v_mul_f32_e32 v11, v9, v7
	v_fma_f32 v13, -v5, v11, v9
	v_fmac_f32_e32 v11, v13, v7
	v_fma_f32 v5, -v5, v11, v9
	v_div_fmas_f32 v5, v5, v7, v11
	v_div_fixup_f32 v3, v5, v3, 1.0
	v_div_scale_f32 v8, vcc, 1.0, v2, 1.0
	v_mul_f32_e32 v10, v8, v6
	v_fma_f32 v12, -v4, v10, v8
	v_fmac_f32_e32 v10, v12, v6
	v_fma_f32 v4, -v4, v10, v8
	v_div_fmas_f32 v4, v4, v6, v10
	v_div_fixup_f32 v2, v4, v2, 1.0
	v_lshlrev_b32_e32 v14, 16, v151
	v_and_b32_e32 v15, 0xffff0000, v151
	v_lshlrev_b32_e32 v16, 16, v229
	v_and_b32_e32 v17, 0xffff0000, v229
	v_fma_f32 v2, v2, v14, v16
	v_fma_f32 v3, v3, v15, v17
	v_cvt_pk_bf16_f32 v159, v2, v3
	global_load_dwordx4 v[186:189], v160, s[60:61]
	global_load_dwordx4 v[226:229], v19, s[62:63]
	s_add_u32 s60, s60, 0x51000
	s_addc_u32 s61, s61, 0
	s_add_u32 s62, s62, 0x10000
	s_addc_u32 s63, s63, 0
	global_store_dwordx4 v19, v[156:159], s[64:65]
	s_add_u32 s64, s64, 0x10000
	s_addc_u32 s65, s65, 0
	ds_read_b128 v[148:151], v18
	v_add_u32_e32 v18, 0x2100, v18
	s_waitcnt vmcnt(7)
	v_lshlrev_b32_e32 v2, 16, v190
	v_and_b32_e32 v3, 0xffff0000, v190
	v_mul_f32_e32 v2, 0xbfb8aa3b, v2
	v_mul_f32_e32 v3, 0xbfb8aa3b, v3
	v_exp_f32_e32 v2, v2
	v_exp_f32_e32 v3, v3
	v_add_f32_e32 v2, 1.0, v2
	v_add_f32_e32 v3, 1.0, v3
	v_div_scale_f32 v5, s[30:31], v3, v3, 1.0
	v_div_scale_f32 v4, s[30:31], v2, v2, 1.0
	v_rcp_f32_e32 v7, v5
	v_rcp_f32_e32 v6, v4
	v_fma_f32 v9, -v5, v7, 1.0
	v_fma_f32 v8, -v4, v6, 1.0
	v_fmac_f32_e32 v7, v9, v7
	v_fmac_f32_e32 v6, v8, v6
	v_div_scale_f32 v9, vcc, 1.0, v3, 1.0
	v_mul_f32_e32 v11, v9, v7
	v_fma_f32 v13, -v5, v11, v9
	v_fmac_f32_e32 v11, v13, v7
	v_fma_f32 v5, -v5, v11, v9
	v_div_fmas_f32 v5, v5, v7, v11
	v_div_fixup_f32 v3, v5, v3, 1.0
	v_div_scale_f32 v8, vcc, 1.0, v2, 1.0
	v_mul_f32_e32 v10, v8, v6
	v_fma_f32 v12, -v4, v10, v8
	v_fmac_f32_e32 v10, v12, v6
	v_fma_f32 v4, -v4, v10, v8
	v_div_fmas_f32 v4, v4, v6, v10
	v_div_fixup_f32 v2, v4, v2, 1.0
	s_waitcnt lgkmcnt(0)
; __device__ __forceinline__ float sigmoid_f(float x) { return 1.f / (1.f + __expf(-x)); }
; template <int NT, int BM, int BN, bool PLAIN, int NSTAGE, bool EPI_LDS>
; __device__ __forceinline__ void gemm_tile(const Params& p, const GemmDesc& g, bf16_t* lds, const int tid) {
;     ...
;     const long ldo = (g.epi == E_PROJ) ? LDP : (g.epi == E_RELU2 ? 8192 : 2048);
;     const int gcol = COL_BG + g.auxi * 2048;
; #pragma unroll 4
;     for (int i = 0; i < NIT; ++i) {
;       const int id = tid + NT * i;
;       const int row = id / PPR, pc = id % PPR;
;       u32x4 v = *(const u32x4*)(ct + row * CST + pc * 8);
;       bf16_t* op = o + (long)(m0e + row) * ldo + n0e + pc * 8;
;       if (g.epi == E_MERGE0 || g.epi == E_MERGEN) {
;         const u32x4 gt = *(const u32x4*)(((bf16_t*)(p.ws + OFF_proj)) + (long)(m0e + row) * LDP + gcol + n0e + pc * 8);
;         u32x4 pv = u32x4{0u, 0u, 0u, 0u};
;         if (g.epi == E_MERGEN) pv = *(const u32x4*)op;
; #pragma unroll
;         for (int e = 0; e < 4; ++e) {
;           const float g0 = sigmoid_f(__uint_as_float(gt[e] << 16)), g1 = sigmoid_f(__uint_as_float(gt[e] & 0xffff0000u));
;           const float a0 = __uint_as_float(v[e] << 16), a1 = __uint_as_float(v[e] & 0xffff0000u);
;           const float p0 = __uint_as_float(pv[e] << 16), p1 = __uint_as_float(pv[e] & 0xffff0000u);
;           v[e] = pack2(p0 + g0 * a0, p1 + g1 * a1);
;         }
;       }
;       *(u32x4*)op = v;
	v_lshlrev_b32_e32 v14, 16, v148
	v_and_b32_e32 v15, 0xffff0000, v148
	v_lshlrev_b32_e32 v16, 16, v230
	v_and_b32_e32 v17, 0xffff0000, v230
	v_fma_f32 v2, v2, v14, v16
	v_fma_f32 v3, v3, v15, v17
	v_cvt_pk_bf16_f32 v156, v2, v3
	v_lshlrev_b32_e32 v2, 16, v191
	v_and_b32_e32 v3, 0xffff0000, v191
	v_mul_f32_e32 v2, 0xbfb8aa3b, v2
	v_mul_f32_e32 v3, 0xbfb8aa3b, v3
	v_exp_f32_e32 v2, v2
	v_exp_f32_e32 v3, v3
	v_add_f32_e32 v2, 1.0, v2
	v_add_f32_e32 v3, 1.0, v3
	v_div_scale_f32 v5, s[30:31], v3, v3, 1.0
	v_div_scale_f32 v4, s[30:31], v2, v2, 1.0
	v_rcp_f32_e32 v7, v5
	v_rcp_f32_e32 v6, v4
	v_fma_f32 v9, -v5, v7, 1.0
	v_fma_f32 v8, -v4, v6, 1.0
	v_fmac_f32_e32 v7, v9, v7
	v_fmac_f32_e32 v6, v8, v6
	v_div_scale_f32 v9, vcc, 1.0, v3, 1.0
	v_mul_f32_e32 v11, v9, v7
	v_fma_f32 v13, -v5, v11, v9
	v_fmac_f32_e32 v11, v13, v7
	v_fma_f32 v5, -v5, v11, v9
	v_div_fmas_f32 v5, v5, v7, v11
	v_div_fixup_f32 v3, v5, v3, 1.0
	v_div_scale_f32 v8, vcc, 1.0, v2, 1.0
	v_mul_f32_e32 v10, v8, v6
	v_fma_f32 v12, -v4, v10, v8
	v_fmac_f32_e32 v10, v12, v6
	v_fma_f32 v4, -v4, v10, v8
	v_div_fmas_f32 v4, v4, v6, v10
	v_div_fixup_f32 v2, v4, v2, 1.0
	v_lshlrev_b32_e32 v14, 16, v149
	v_and_b32_e32 v15, 0xffff0000, v149
	v_lshlrev_b32_e32 v16, 16, v231
	v_and_b32_e32 v17, 0xffff0000, v231
	v_fma_f32 v2, v2, v14, v16
	v_fma_f32 v3, v3, v15, v17
	v_cvt_pk_bf16_f32 v157, v2, v3
	v_lshlrev_b32_e32 v2, 16, v192
	v_and_b32_e32 v3, 0xffff0000, v192
	v_mul_f32_e32 v2, 0xbfb8aa3b, v2
	v_mul_f32_e32 v3, 0xbfb8aa3b, v3
	v_exp_f32_e32 v2, v2
	v_exp_f32_e32 v3, v3
	v_add_f32_e32 v2, 1.0, v2
	v_add_f32_e32 v3, 1.0, v3
	v_div_scale_f32 v5, s[30:31], v3, v3, 1.0
	v_div_scale_f32 v4, s[30:31], v2, v2, 1.0
	v_rcp_f32_e32 v7, v5
	v_rcp_f32_e32 v6, v4
	v_fma_f32 v9, -v5, v7, 1.0
	v_fma_f32 v8, -v4, v6, 1.0
	v_fmac_f32_e32 v7, v9, v7
	v_fmac_f32_e32 v6, v8, v6
	v_div_scale_f32 v9, vcc, 1.0, v3, 1.0
	v_mul_f32_e32 v11, v9, v7
	v_fma_f32 v13, -v5, v11, v9
	v_fmac_f32_e32 v11, v13, v7
	v_fma_f32 v5, -v5, v11, v9
	v_div_fmas_f32 v5, v5, v7, v11
	v_div_fixup_f32 v3, v5, v3, 1.0
	v_div_scale_f32 v8, vcc, 1.0, v2, 1.0
	v_mul_f32_e32 v10, v8, v6
	v_fma_f32 v12, -v4, v10, v8
	v_fmac_f32_e32 v10, v12, v6
	v_fma_f32 v4, -v4, v10, v8
	v_div_fmas_f32 v4, v4, v6, v10
	v_div_fixup_f32 v2, v4, v2, 1.0
	v_lshlrev_b32_e32 v14, 16, v150
	v_and_b32_e32 v15, 0xffff0000, v150
	v_lshlrev_b32_e32 v16, 16, v232
	v_and_b32_e32 v17, 0xffff0000, v232
	v_fma_f32 v2, v2, v14, v16
	v_fma_f32 v3, v3, v15, v17
	v_cvt_pk_bf16_f32 v158, v2, v3
	v_lshlrev_b32_e32 v2, 16, v193
	v_and_b32_e32 v3, 0xffff0000, v193
	v_mul_f32_e32 v2, 0xbfb8aa3b, v2
	v_mul_f32_e32 v3, 0xbfb8aa3b, v3
	v_exp_f32_e32 v2, v2
	v_exp_f32_e32 v3, v3
	v_add_f32_e32 v2, 1.0, v2
	v_add_f32_e32 v3, 1.0, v3
	v_div_scale_f32 v5, s[30:31], v3, v3, 1.0
	v_div_scale_f32 v4, s[30:31], v2, v2, 1.0
	v_rcp_f32_e32 v7, v5
	v_rcp_f32_e32 v6, v4
	v_fma_f32 v9, -v5, v7, 1.0
	v_fma_f32 v8, -v4, v6, 1.0
	v_fmac_f32_e32 v7, v9, v7
	v_fmac_f32_e32 v6, v8, v6
	v_div_scale_f32 v9, vcc, 1.0, v3, 1.0
	v_mul_f32_e32 v11, v9, v7
	v_fma_f32 v13, -v5, v11, v9
	v_fmac_f32_e32 v11, v13, v7
	v_fma_f32 v5, -v5, v11, v9
	v_div_fmas_f32 v5, v5, v7, v11
	v_div_fixup_f32 v3, v5, v3, 1.0
	v_div_scale_f32 v8, vcc, 1.0, v2, 1.0
	v_mul_f32_e32 v10, v8, v6
	v_fma_f32 v12, -v4, v10, v8
	v_fmac_f32_e32 v10, v12, v6
	v_fma_f32 v4, -v4, v10, v8
	v_div_fmas_f32 v4, v4, v6, v10
	v_div_fixup_f32 v2, v4, v2, 1.0
	v_lshlrev_b32_e32 v14, 16, v151
	v_and_b32_e32 v15, 0xffff0000, v151
	v_lshlrev_b32_e32 v16, 16, v233
	v_and_b32_e32 v17, 0xffff0000, v233
	v_fma_f32 v2, v2, v14, v16
	v_fma_f32 v3, v3, v15, v17
	v_cvt_pk_bf16_f32 v159, v2, v3
	global_load_dwordx4 v[190:193], v160, s[60:61]
	global_load_dwordx4 v[230:233], v19, s[62:63]
	s_add_u32 s60, s60, 0x51000
	s_addc_u32 s61, s61, 0
	s_add_u32 s62, s62, 0x10000
	s_addc_u32 s63, s63, 0
	global_store_dwordx4 v19, v[156:159], s[64:65]
	s_add_u32 s64, s64, 0x10000
	s_addc_u32 s65, s65, 0
	ds_read_b128 v[148:151], v18
	v_add_u32_e32 v18, 0x2100, v18
	s_waitcnt vmcnt(8)
	v_lshlrev_b32_e32 v2, 16, v194
	v_and_b32_e32 v3, 0xffff0000, v194
	v_mul_f32_e32 v2, 0xbfb8aa3b, v2
	v_mul_f32_e32 v3, 0xbfb8aa3b, v3
	v_exp_f32_e32 v2, v2
	v_exp_f32_e32 v3, v3
	v_add_f32_e32 v2, 1.0, v2
	v_add_f32_e32 v3, 1.0, v3
	v_div_scale_f32 v5, s[30:31], v3, v3, 1.0
	v_div_scale_f32 v4, s[30:31], v2, v2, 1.0
	v_rcp_f32_e32 v7, v5
	v_rcp_f32_e32 v6, v4
	v_fma_f32 v9, -v5, v7, 1.0
	v_fma_f32 v8, -v4, v6, 1.0
	v_fmac_f32_e32 v7, v9, v7
	v_fmac_f32_e32 v6, v8, v6
	v_div_scale_f32 v9, vcc, 1.0, v3, 1.0
	v_mul_f32_e32 v11, v9, v7
	v_fma_f32 v13, -v5, v11, v9
	v_fmac_f32_e32 v11, v13, v7
	v_fma_f32 v5, -v5, v11, v9
	v_div_fmas_f32 v5, v5, v7, v11
	v_div_fixup_f32 v3, v5, v3, 1.0
	v_div_scale_f32 v8, vcc, 1.0, v2, 1.0
	v_mul_f32_e32 v10, v8, v6
	v_fma_f32 v12, -v4, v10, v8
	v_fmac_f32_e32 v10, v12, v6
	v_fma_f32 v4, -v4, v10, v8
	v_div_fmas_f32 v4, v4, v6, v10
	v_div_fixup_f32 v2, v4, v2, 1.0
	s_waitcnt lgkmcnt(0)
; __device__ __forceinline__ float sigmoid_f(float x) { return 1.f / (1.f + __expf(-x)); }
; template <int NT, int BM, int BN, bool PLAIN, int NSTAGE, bool EPI_LDS>
; __device__ __forceinline__ void gemm_tile(const Params& p, const GemmDesc& g, bf16_t* lds, const int tid) {
;     ...
;     const long ldo = (g.epi == E_PROJ) ? LDP : (g.epi == E_RELU2 ? 8192 : 2048);
;     const int gcol = COL_BG + g.auxi * 2048;
; #pragma unroll 4
;     for (int i = 0; i < NIT; ++i) {
;       const int id = tid + NT * i;
;       const int row = id / PPR, pc = id % PPR;
;       u32x4 v = *(const u32x4*)(ct + row * CST + pc * 8);
;       bf16_t* op = o + (long)(m0e + row) * ldo + n0e + pc * 8;
;       if (g.epi == E_MERGE0 || g.epi == E_MERGEN) {
;         const u32x4 gt = *(const u32x4*)(((bf16_t*)(p.ws + OFF_proj)) + (long)(m0e + row) * LDP + gcol + n0e + pc * 8);
;         u32x4 pv = u32x4{0u, 0u, 0u, 0u};
;         if (g.epi == E_MERGEN) pv = *(const u32x4*)op;
; #pragma unroll
;         for (int e = 0; e < 4; ++e) {
;           const float g0 = sigmoid_f(__uint_as_float(gt[e] << 16)), g1 = sigmoid_f(__uint_as_float(gt[e] & 0xffff0000u));
;           const float a0 = __uint_as_float(v[e] << 16), a1 = __uint_as_float(v[e] & 0xffff0000u);
;           const float p0 = __uint_as_float(pv[e] << 16), p1 = __uint_as_float(pv[e] & 0xffff0000u);
;           v[e] = pack2(p0 + g0 * a0, p1 + g1 * a1);
;         }
;       }
;       *(u32x4*)op = v;
	v_lshlrev_b32_e32 v14, 16, v148
	v_and_b32_e32 v15, 0xffff0000, v148
	v_lshlrev_b32_e32 v16, 16, v234
	v_and_b32_e32 v17, 0xffff0000, v234
	v_fma_f32 v2, v2, v14, v16
	v_fma_f32 v3, v3, v15, v17
	v_cvt_pk_bf16_f32 v156, v2, v3
	v_lshlrev_b32_e32 v2, 16, v195
	v_and_b32_e32 v3, 0xffff0000, v195
	v_mul_f32_e32 v2, 0xbfb8aa3b, v2
	v_mul_f32_e32 v3, 0xbfb8aa3b, v3
	v_exp_f32_e32 v2, v2
	v_exp_f32_e32 v3, v3
	v_add_f32_e32 v2, 1.0, v2
	v_add_f32_e32 v3, 1.0, v3
	v_div_scale_f32 v5, s[30:31], v3, v3, 1.0
	v_div_scale_f32 v4, s[30:31], v2, v2, 1.0
	v_rcp_f32_e32 v7, v5
	v_rcp_f32_e32 v6, v4
	v_fma_f32 v9, -v5, v7, 1.0
	v_fma_f32 v8, -v4, v6, 1.0
	v_fmac_f32_e32 v7, v9, v7
	v_fmac_f32_e32 v6, v8, v6
	v_div_scale_f32 v9, vcc, 1.0, v3, 1.0
	v_mul_f32_e32 v11, v9, v7
	v_fma_f32 v13, -v5, v11, v9
	v_fmac_f32_e32 v11, v13, v7
	v_fma_f32 v5, -v5, v11, v9
	v_div_fmas_f32 v5, v5, v7, v11
	v_div_fixup_f32 v3, v5, v3, 1.0
	v_div_scale_f32 v8, vcc, 1.0, v2, 1.0
	v_mul_f32_e32 v10, v8, v6
	v_fma_f32 v12, -v4, v10, v8
	v_fmac_f32_e32 v10, v12, v6
	v_fma_f32 v4, -v4, v10, v8
	v_div_fmas_f32 v4, v4, v6, v10
	v_div_fixup_f32 v2, v4, v2, 1.0
	v_lshlrev_b32_e32 v14, 16, v149
	v_and_b32_e32 v15, 0xffff0000, v149
	v_lshlrev_b32_e32 v16, 16, v235
	v_and_b32_e32 v17, 0xffff0000, v235
	v_fma_f32 v2, v2, v14, v16
	v_fma_f32 v3, v3, v15, v17
	v_cvt_pk_bf16_f32 v157, v2, v3
	v_lshlrev_b32_e32 v2, 16, v196
	v_and_b32_e32 v3, 0xffff0000, v196
	v_mul_f32_e32 v2, 0xbfb8aa3b, v2
	v_mul_f32_e32 v3, 0xbfb8aa3b, v3
	v_exp_f32_e32 v2, v2
	v_exp_f32_e32 v3, v3
	v_add_f32_e32 v2, 1.0, v2
	v_add_f32_e32 v3, 1.0, v3
	v_div_scale_f32 v5, s[30:31], v3, v3, 1.0
	v_div_scale_f32 v4, s[30:31], v2, v2, 1.0
	v_rcp_f32_e32 v7, v5
	v_rcp_f32_e32 v6, v4
	v_fma_f32 v9, -v5, v7, 1.0
	v_fma_f32 v8, -v4, v6, 1.0
	v_fmac_f32_e32 v7, v9, v7
	v_fmac_f32_e32 v6, v8, v6
	v_div_scale_f32 v9, vcc, 1.0, v3, 1.0
	v_mul_f32_e32 v11, v9, v7
	v_fma_f32 v13, -v5, v11, v9
	v_fmac_f32_e32 v11, v13, v7
	v_fma_f32 v5, -v5, v11, v9
	v_div_fmas_f32 v5, v5, v7, v11
	v_div_fixup_f32 v3, v5, v3, 1.0
	v_div_scale_f32 v8, vcc, 1.0, v2, 1.0
	v_mul_f32_e32 v10, v8, v6
	v_fma_f32 v12, -v4, v10, v8
	v_fmac_f32_e32 v10, v12, v6
	v_fma_f32 v4, -v4, v10, v8
	v_div_fmas_f32 v4, v4, v6, v10
	v_div_fixup_f32 v2, v4, v2, 1.0
	v_lshlrev_b32_e32 v14, 16, v150
	v_and_b32_e32 v15, 0xffff0000, v150
	v_lshlrev_b32_e32 v16, 16, v236
	v_and_b32_e32 v17, 0xffff0000, v236
	v_fma_f32 v2, v2, v14, v16
	v_fma_f32 v3, v3, v15, v17
	v_cvt_pk_bf16_f32 v158, v2, v3
	v_lshlrev_b32_e32 v2, 16, v197
	v_and_b32_e32 v3, 0xffff0000, v197
	v_mul_f32_e32 v2, 0xbfb8aa3b, v2
	v_mul_f32_e32 v3, 0xbfb8aa3b, v3
	v_exp_f32_e32 v2, v2
	v_exp_f32_e32 v3, v3
	v_add_f32_e32 v2, 1.0, v2
	v_add_f32_e32 v3, 1.0, v3
	v_div_scale_f32 v5, s[30:31], v3, v3, 1.0
	v_div_scale_f32 v4, s[30:31], v2, v2, 1.0
	v_rcp_f32_e32 v7, v5
	v_rcp_f32_e32 v6, v4
	v_fma_f32 v9, -v5, v7, 1.0
	v_fma_f32 v8, -v4, v6, 1.0
	v_fmac_f32_e32 v7, v9, v7
	v_fmac_f32_e32 v6, v8, v6
	v_div_scale_f32 v9, vcc, 1.0, v3, 1.0
	v_mul_f32_e32 v11, v9, v7
	v_fma_f32 v13, -v5, v11, v9
	v_fmac_f32_e32 v11, v13, v7
	v_fma_f32 v5, -v5, v11, v9
	v_div_fmas_f32 v5, v5, v7, v11
	v_div_fixup_f32 v3, v5, v3, 1.0
	v_div_scale_f32 v8, vcc, 1.0, v2, 1.0
	v_mul_f32_e32 v10, v8, v6
	v_fma_f32 v12, -v4, v10, v8
	v_fmac_f32_e32 v10, v12, v6
	v_fma_f32 v4, -v4, v10, v8
	v_div_fmas_f32 v4, v4, v6, v10
	v_div_fixup_f32 v2, v4, v2, 1.0
	v_lshlrev_b32_e32 v14, 16, v151
	v_and_b32_e32 v15, 0xffff0000, v151
	v_lshlrev_b32_e32 v16, 16, v237
	v_and_b32_e32 v17, 0xffff0000, v237
	v_fma_f32 v2, v2, v14, v16
	v_fma_f32 v3, v3, v15, v17
	v_cvt_pk_bf16_f32 v159, v2, v3
	global_load_dwordx4 v[194:197], v160, s[60:61]
	global_load_dwordx4 v[234:237], v19, s[62:63]
	s_add_u32 s60, s60, 0x51000
	s_addc_u32 s61, s61, 0
	s_add_u32 s62, s62, 0x10000
	s_addc_u32 s63, s63, 0
	global_store_dwordx4 v19, v[156:159], s[64:65]
	s_add_u32 s64, s64, 0x10000
	s_addc_u32 s65, s65, 0
	ds_read_b128 v[148:151], v18
	v_add_u32_e32 v18, 0x2100, v18
	s_waitcnt vmcnt(9)
	v_lshlrev_b32_e32 v2, 16, v198
	v_and_b32_e32 v3, 0xffff0000, v198
	v_mul_f32_e32 v2, 0xbfb8aa3b, v2
	v_mul_f32_e32 v3, 0xbfb8aa3b, v3
	v_exp_f32_e32 v2, v2
	v_exp_f32_e32 v3, v3
	v_add_f32_e32 v2, 1.0, v2
	v_add_f32_e32 v3, 1.0, v3
	v_div_scale_f32 v5, s[30:31], v3, v3, 1.0
	v_div_scale_f32 v4, s[30:31], v2, v2, 1.0
	v_rcp_f32_e32 v7, v5
	v_rcp_f32_e32 v6, v4
	v_fma_f32 v9, -v5, v7, 1.0
	v_fma_f32 v8, -v4, v6, 1.0
	v_fmac_f32_e32 v7, v9, v7
	v_fmac_f32_e32 v6, v8, v6
	v_div_scale_f32 v9, vcc, 1.0, v3, 1.0
	v_mul_f32_e32 v11, v9, v7
	v_fma_f32 v13, -v5, v11, v9
	v_fmac_f32_e32 v11, v13, v7
	v_fma_f32 v5, -v5, v11, v9
	v_div_fmas_f32 v5, v5, v7, v11
	v_div_fixup_f32 v3, v5, v3, 1.0
	v_div_scale_f32 v8, vcc, 1.0, v2, 1.0
	v_mul_f32_e32 v10, v8, v6
	v_fma_f32 v12, -v4, v10, v8
	v_fmac_f32_e32 v10, v12, v6
	v_fma_f32 v4, -v4, v10, v8
	v_div_fmas_f32 v4, v4, v6, v10
	v_div_fixup_f32 v2, v4, v2, 1.0
	s_waitcnt lgkmcnt(0)
; __device__ __forceinline__ float sigmoid_f(float x) { return 1.f / (1.f + __expf(-x)); }
; template <int NT, int BM, int BN, bool PLAIN, int NSTAGE, bool EPI_LDS>
; __device__ __forceinline__ void gemm_tile(const Params& p, const GemmDesc& g, bf16_t* lds, const int tid) {
;     ...
;     const long ldo = (g.epi == E_PROJ) ? LDP : (g.epi == E_RELU2 ? 8192 : 2048);
;     const int gcol = COL_BG + g.auxi * 2048;
; #pragma unroll 4
;     for (int i = 0; i < NIT; ++i) {
;       const int id = tid + NT * i;
;       const int row = id / PPR, pc = id % PPR;
;       u32x4 v = *(const u32x4*)(ct + row * CST + pc * 8);
;       bf16_t* op = o + (long)(m0e + row) * ldo + n0e + pc * 8;
;       if (g.epi == E_MERGE0 || g.epi == E_MERGEN) {
;         const u32x4 gt = *(const u32x4*)(((bf16_t*)(p.ws + OFF_proj)) + (long)(m0e + row) * LDP + gcol + n0e + pc * 8);
;         u32x4 pv = u32x4{0u, 0u, 0u, 0u};
;         if (g.epi == E_MERGEN) pv = *(const u32x4*)op;
; #pragma unroll
;         for (int e = 0; e < 4; ++e) {
;           const float g0 = sigmoid_f(__uint_as_float(gt[e] << 16)), g1 = sigmoid_f(__uint_as_float(gt[e] & 0xffff0000u));
;           const float a0 = __uint_as_float(v[e] << 16), a1 = __uint_as_float(v[e] & 0xffff0000u);
;           const float p0 = __uint_as_float(pv[e] << 16), p1 = __uint_as_float(pv[e] & 0xffff0000u);
;           v[e] = pack2(p0 + g0 * a0, p1 + g1 * a1);
;         }
;       }
;       *(u32x4*)op = v;
	v_lshlrev_b32_e32 v14, 16, v148
	v_and_b32_e32 v15, 0xffff0000, v148
	v_lshlrev_b32_e32 v16, 16, v238
	v_and_b32_e32 v17, 0xffff0000, v238
	v_fma_f32 v2, v2, v14, v16
	v_fma_f32 v3, v3, v15, v17
	v_cvt_pk_bf16_f32 v156, v2, v3
	v_lshlrev_b32_e32 v2, 16, v199
	v_and_b32_e32 v3, 0xffff0000, v199
	v_mul_f32_e32 v2, 0xbfb8aa3b, v2
	v_mul_f32_e32 v3, 0xbfb8aa3b, v3
	v_exp_f32_e32 v2, v2
	v_exp_f32_e32 v3, v3
	v_add_f32_e32 v2, 1.0, v2
	v_add_f32_e32 v3, 1.0, v3
	v_div_scale_f32 v5, s[30:31], v3, v3, 1.0
	v_div_scale_f32 v4, s[30:31], v2, v2, 1.0
	v_rcp_f32_e32 v7, v5
	v_rcp_f32_e32 v6, v4
	v_fma_f32 v9, -v5, v7, 1.0
	v_fma_f32 v8, -v4, v6, 1.0
	v_fmac_f32_e32 v7, v9, v7
	v_fmac_f32_e32 v6, v8, v6
	v_div_scale_f32 v9, vcc, 1.0, v3, 1.0
	v_mul_f32_e32 v11, v9, v7
	v_fma_f32 v13, -v5, v11, v9
	v_fmac_f32_e32 v11, v13, v7
	v_fma_f32 v5, -v5, v11, v9
	v_div_fmas_f32 v5, v5, v7, v11
	v_div_fixup_f32 v3, v5, v3, 1.0
	v_div_scale_f32 v8, vcc, 1.0, v2, 1.0
	v_mul_f32_e32 v10, v8, v6
	v_fma_f32 v12, -v4, v10, v8
	v_fmac_f32_e32 v10, v12, v6
	v_fma_f32 v4, -v4, v10, v8
	v_div_fmas_f32 v4, v4, v6, v10
	v_div_fixup_f32 v2, v4, v2, 1.0
	v_lshlrev_b32_e32 v14, 16, v149
	v_and_b32_e32 v15, 0xffff0000, v149
	v_lshlrev_b32_e32 v16, 16, v239
	v_and_b32_e32 v17, 0xffff0000, v239
	v_fma_f32 v2, v2, v14, v16
	v_fma_f32 v3, v3, v15, v17
	v_cvt_pk_bf16_f32 v157, v2, v3
	v_lshlrev_b32_e32 v2, 16, v200
	v_and_b32_e32 v3, 0xffff0000, v200
	v_mul_f32_e32 v2, 0xbfb8aa3b, v2
	v_mul_f32_e32 v3, 0xbfb8aa3b, v3
	v_exp_f32_e32 v2, v2
	v_exp_f32_e32 v3, v3
	v_add_f32_e32 v2, 1.0, v2
	v_add_f32_e32 v3, 1.0, v3
	v_div_scale_f32 v5, s[30:31], v3, v3, 1.0
	v_div_scale_f32 v4, s[30:31], v2, v2, 1.0
	v_rcp_f32_e32 v7, v5
	v_rcp_f32_e32 v6, v4
	v_fma_f32 v9, -v5, v7, 1.0
	v_fma_f32 v8, -v4, v6, 1.0
	v_fmac_f32_e32 v7, v9, v7
	v_fmac_f32_e32 v6, v8, v6
	v_div_scale_f32 v9, vcc, 1.0, v3, 1.0
	v_mul_f32_e32 v11, v9, v7
	v_fma_f32 v13, -v5, v11, v9
	v_fmac_f32_e32 v11, v13, v7
	v_fma_f32 v5, -v5, v11, v9
	v_div_fmas_f32 v5, v5, v7, v11
	v_div_fixup_f32 v3, v5, v3, 1.0
	v_div_scale_f32 v8, vcc, 1.0, v2, 1.0
	v_mul_f32_e32 v10, v8, v6
	v_fma_f32 v12, -v4, v10, v8
	v_fmac_f32_e32 v10, v12, v6
	v_fma_f32 v4, -v4, v10, v8
	v_div_fmas_f32 v4, v4, v6, v10
	v_div_fixup_f32 v2, v4, v2, 1.0
	v_lshlrev_b32_e32 v14, 16, v150
	v_and_b32_e32 v15, 0xffff0000, v150
	v_lshlrev_b32_e32 v16, 16, v240
	v_and_b32_e32 v17, 0xffff0000, v240
	v_fma_f32 v2, v2, v14, v16
	v_fma_f32 v3, v3, v15, v17
	v_cvt_pk_bf16_f32 v158, v2, v3
	v_lshlrev_b32_e32 v2, 16, v201
	v_and_b32_e32 v3, 0xffff0000, v201
	v_mul_f32_e32 v2, 0xbfb8aa3b, v2
	v_mul_f32_e32 v3, 0xbfb8aa3b, v3
	v_exp_f32_e32 v2, v2
	v_exp_f32_e32 v3, v3
	v_add_f32_e32 v2, 1.0, v2
	v_add_f32_e32 v3, 1.0, v3
	v_div_scale_f32 v5, s[30:31], v3, v3, 1.0
	v_div_scale_f32 v4, s[30:31], v2, v2, 1.0
	v_rcp_f32_e32 v7, v5
	v_rcp_f32_e32 v6, v4
	v_fma_f32 v9, -v5, v7, 1.0
	v_fma_f32 v8, -v4, v6, 1.0
	v_fmac_f32_e32 v7, v9, v7
	v_fmac_f32_e32 v6, v8, v6
	v_div_scale_f32 v9, vcc, 1.0, v3, 1.0
	v_mul_f32_e32 v11, v9, v7
	v_fma_f32 v13, -v5, v11, v9
	v_fmac_f32_e32 v11, v13, v7
	v_fma_f32 v5, -v5, v11, v9
	v_div_fmas_f32 v5, v5, v7, v11
	v_div_fixup_f32 v3, v5, v3, 1.0
	v_div_scale_f32 v8, vcc, 1.0, v2, 1.0
	v_mul_f32_e32 v10, v8, v6
	v_fma_f32 v12, -v4, v10, v8
	v_fmac_f32_e32 v10, v12, v6
	v_fma_f32 v4, -v4, v10, v8
	v_div_fmas_f32 v4, v4, v6, v10
	v_div_fixup_f32 v2, v4, v2, 1.0
	v_lshlrev_b32_e32 v14, 16, v151
	v_and_b32_e32 v15, 0xffff0000, v151
	v_lshlrev_b32_e32 v16, 16, v241
	v_and_b32_e32 v17, 0xffff0000, v241
	v_fma_f32 v2, v2, v14, v16
	v_fma_f32 v3, v3, v15, v17
	v_cvt_pk_bf16_f32 v159, v2, v3
	global_load_dwordx4 v[198:201], v160, s[60:61]
	global_load_dwordx4 v[238:241], v19, s[62:63]
	s_add_u32 s60, s60, 0x51000
	s_addc_u32 s61, s61, 0
	s_add_u32 s62, s62, 0x10000
	s_addc_u32 s63, s63, 0
	global_store_dwordx4 v19, v[156:159], s[64:65]
	s_add_u32 s64, s64, 0x10000
	s_addc_u32 s65, s65, 0
	s_add_i32 s57, s57, 1
	s_cmp_eq_u32 s57, 3
	s_cselect_b32 s0, 0x510000, 0
	s_cselect_b32 s2, 0x100000, 0
	s_sub_u32 s60, s60, s0
	s_subb_u32 s61, s61, 0
	s_sub_u32 s62, s62, s2
	s_subb_u32 s63, s63, 0
	s_cmp_lt_u32 s57, 4
	s_cbranch_scc1 .Lmy_mergeN_loop
	s_branch .LBB0_888
; __device__ __forceinline__ float sigmoid_f(float x) { return 1.f / (1.f + __expf(-x)); }
; template <int NT, int BM, int BN, bool PLAIN, int NSTAGE, bool EPI_LDS>
; __device__ __forceinline__ void gemm_tile(const Params& p, const GemmDesc& g, bf16_t* lds, const int tid) {
;     ...
; #pragma unroll 4
;     for (int i = 0; i < NIT; ++i) {
;       const int id = tid + NT * i;
;       const int row = id / PPR, pc = id % PPR;
;       u32x4 v = *(const u32x4*)(ct + row * CST + pc * 8);
;       bf16_t* op = o + (long)(m0e + row) * ldo + n0e + pc * 8;
;       if (g.epi == E_MERGE0 || g.epi == E_MERGEN) {
;         const u32x4 gt = *(const u32x4*)(((bf16_t*)(p.ws + OFF_proj)) + (long)(m0e + row) * LDP + gcol + n0e + pc * 8);
;         u32x4 pv = u32x4{0u, 0u, 0u, 0u};
;         if (g.epi == E_MERGEN) pv = *(const u32x4*)op;
; #pragma unroll
;         for (int e = 0; e < 4; ++e) {
;           const float g0 = sigmoid_f(__uint_as_float(gt[e] << 16)), g1 = sigmoid_f(__uint_as_float(gt[e] & 0xffff0000u));
;           const float a0 = __uint_as_float(v[e] << 16), a1 = __uint_as_float(v[e] & 0xffff0000u);
;           const float p0 = __uint_as_float(pv[e] << 16), p1 = __uint_as_float(pv[e] & 0xffff0000u);
;           v[e] = pack2(p0 + g0 * a0, p1 + g1 * a1);
;         }
;       }
;       *(u32x4*)op = v;
.Lmy_plain:
	v_lshrrev_b32_e32 v2, 5, v224
	v_and_b32_e32 v3, 31, v224
	v_lshlrev_b32_e32 v3, 4, v3
	v_mul_u32_u24_e32 v18, 0x210, v2
	v_add_u32_e32 v18, v18, v3
	v_add_u32_e32 v17, 0x10800, v18
	v_add_u32_e32 v2, s23, v2
	s_lshl_b32 s0, s58, 1
	v_mul_lo_u32 v19, v2, s0
	v_add_u32_e32 v19, v19, v3
	s_lshl_b32 s0, s58, 5
	s_mov_b64 s[64:65], s[26:27]
	ds_read_b128 v[20:23], v18
	ds_read_b128 v[24:27], v18 offset:8448
	ds_read_b128 v[28:31], v18 offset:16896
	ds_read_b128 v[32:35], v18 offset:25344
	ds_read_b128 v[36:39], v18 offset:33792
	ds_read_b128 v[40:43], v18 offset:42240
	ds_read_b128 v[44:47], v18 offset:50688
	ds_read_b128 v[48:51], v18 offset:59136
	ds_read_b128 v[52:55], v17
	s_waitcnt lgkmcnt(8)
	global_store_dwordx4 v19, v[20:23], s[64:65]
	s_add_u32 s64, s64, s0
	s_addc_u32 s65, s65, 0
	ds_read_b128 v[56:59], v17 offset:8448
	s_waitcnt lgkmcnt(8)
	global_store_dwordx4 v19, v[24:27], s[64:65]
	s_add_u32 s64, s64, s0
	s_addc_u32 s65, s65, 0
	ds_read_b128 v[60:63], v17 offset:16896
	s_waitcnt lgkmcnt(8)
	global_store_dwordx4 v19, v[28:31], s[64:65]
	s_add_u32 s64, s64, s0
	s_addc_u32 s65, s65, 0
	ds_read_b128 v[64:67], v17 offset:25344
	s_waitcnt lgkmcnt(8)
	global_store_dwordx4 v19, v[32:35], s[64:65]
	s_add_u32 s64, s64, s0
	s_addc_u32 s65, s65, 0
	ds_read_b128 v[68:71], v17 offset:33792
	s_waitcnt lgkmcnt(8)
	global_store_dwordx4 v19, v[36:39], s[64:65]
	s_add_u32 s64, s64, s0
	s_addc_u32 s65, s65, 0
	ds_read_b128 v[72:75], v17 offset:42240
	s_waitcnt lgkmcnt(8)
	global_store_dwordx4 v19, v[40:43], s[64:65]
	s_add_u32 s64, s64, s0
	s_addc_u32 s65, s65, 0
	ds_read_b128 v[76:79], v17 offset:50688
	s_waitcnt lgkmcnt(8)
	global_store_dwordx4 v19, v[44:47], s[64:65]
	s_add_u32 s64, s64, s0
	s_addc_u32 s65, s65, 0
	ds_read_b128 v[80:83], v17 offset:59136
	s_waitcnt lgkmcnt(8)
	global_store_dwordx4 v19, v[48:51], s[64:65]
	s_add_u32 s64, s64, s0
	s_addc_u32 s65, s65, 0
	s_waitcnt lgkmcnt(7)
	global_store_dwordx4 v19, v[52:55], s[64:65]
	s_add_u32 s64, s64, s0
	s_addc_u32 s65, s65, 0
	s_waitcnt lgkmcnt(6)
	global_store_dwordx4 v19, v[56:59], s[64:65]
	s_add_u32 s64, s64, s0
	s_addc_u32 s65, s65, 0
	s_waitcnt lgkmcnt(5)
	global_store_dwordx4 v19, v[60:63], s[64:65]
	s_add_u32 s64, s64, s0
	s_addc_u32 s65, s65, 0
	s_waitcnt lgkmcnt(4)
	global_store_dwordx4 v19, v[64:67], s[64:65]
	s_add_u32 s64, s64, s0
	s_addc_u32 s65, s65, 0
	s_waitcnt lgkmcnt(3)
	global_store_dwordx4 v19, v[68:71], s[64:65]
	s_add_u32 s64, s64, s0
	s_addc_u32 s65, s65, 0
	s_waitcnt lgkmcnt(2)
	global_store_dwordx4 v19, v[72:75], s[64:65]
	s_add_u32 s64, s64, s0
	s_addc_u32 s65, s65, 0
	s_waitcnt lgkmcnt(1)
	global_store_dwordx4 v19, v[76:79], s[64:65]
	s_add_u32 s64, s64, s0
	s_addc_u32 s65, s65, 0
	s_waitcnt lgkmcnt(0)
	global_store_dwordx4 v19, v[80:83], s[64:65]
	s_add_u32 s64, s64, s0
	s_addc_u32 s65, s65, 0
	s_branch .LBB0_888
